# GEMM K-loops: issue LDS-DMA stage loads before the ds_read burst in every load segment (all 8 GEMM phases)
# baseline (speedup 1.0000x reference)
.LBB0_217:
	s_add_u32 s36, s34, 0xfffc0080
	s_addc_u32 s37, s35, -1
	s_cmp_eq_u32 s71, 12
	s_cselect_b32 s39, s7, s37
	s_cselect_b32 s38, s25, s36
	s_cselect_b32 s37, s23, s70
	s_cselect_b32 s36, s68, s69
	v_lshl_add_u64 v[150:151], s[34:35], 0, v[138:139]
	s_add_i32 m0, s31, 0xc000
	s_nop 0
	global_load_lds_dwordx4 v[150:151], off
	v_lshl_add_u64 v[150:151], s[34:35], 0, v[140:141]
	s_add_i32 m0, s31, 0xe000
	s_nop 0
	global_load_lds_dwordx4 v[150:151], off
	ds_read_b128 v[146:149], v155
	ds_read_b128 v[158:161], v155 offset:1024
	ds_read_b128 v[162:165], v155 offset:2048
	ds_read_b128 v[166:169], v155 offset:3072
	ds_read_b128 v[170:173], v156
	ds_read_b128 v[174:177], v156 offset:1024
	ds_read_b128 v[178:181], v156 offset:2048
	ds_read_b128 v[182:185], v156 offset:3072
	ds_read_b128 v[186:189], v157
	ds_read_b128 v[190:193], v157 offset:1024
	ds_read_b128 v[194:197], v157 offset:2048
	ds_read_b128 v[198:201], v157 offset:3072
	ds_read_b128 v[202:205], v157 offset:4096
	ds_read_b128 v[206:209], v157 offset:5120
	ds_read_b128 v[210:213], v157 offset:6144
	ds_read_b128 v[214:217], v157 offset:7168
	s_waitcnt vmcnt(8)
	s_waitcnt lgkmcnt(0)
	s_barrier
	s_setprio 1
	s_waitcnt lgkmcnt(0)
	v_mfma_f32_16x16x32_bf16 v[124:127], v[146:149], v[186:189], v[124:127]
	v_mfma_f32_16x16x32_bf16 v[120:123], v[162:165], v[186:189], v[120:123]
	v_mfma_f32_16x16x32_bf16 v[108:111], v[146:149], v[194:197], v[108:111]
	v_mfma_f32_16x16x32_bf16 v[104:107], v[162:165], v[194:197], v[104:107]
	v_mfma_f32_16x16x32_bf16 v[92:95], v[146:149], v[202:205], v[92:95]
	v_mfma_f32_16x16x32_bf16 v[88:91], v[162:165], v[202:205], v[88:91]
	v_mfma_f32_16x16x32_bf16 v[76:79], v[146:149], v[210:213], v[76:79]
	v_mfma_f32_16x16x32_bf16 v[72:75], v[162:165], v[210:213], v[72:75]
	v_mfma_f32_16x16x32_bf16 v[124:127], v[158:161], v[190:193], v[124:127]
	v_mfma_f32_16x16x32_bf16 v[120:123], v[166:169], v[190:193], v[120:123]
	v_mfma_f32_16x16x32_bf16 v[108:111], v[158:161], v[198:201], v[108:111]
	v_mfma_f32_16x16x32_bf16 v[104:107], v[166:169], v[198:201], v[104:107]
	v_mfma_f32_16x16x32_bf16 v[92:95], v[158:161], v[206:209], v[92:95]
	v_mfma_f32_16x16x32_bf16 v[88:91], v[166:169], v[206:209], v[88:91]
	v_mfma_f32_16x16x32_bf16 v[76:79], v[158:161], v[214:217], v[76:79]
	v_mfma_f32_16x16x32_bf16 v[72:75], v[166:169], v[214:217], v[72:75]
	s_setprio 0
	s_setprio 1
	v_mfma_f32_16x16x32_bf16 v[116:119], v[170:173], v[186:189], v[116:119]
	v_mfma_f32_16x16x32_bf16 v[112:115], v[178:181], v[186:189], v[112:115]
	v_mfma_f32_16x16x32_bf16 v[100:103], v[170:173], v[194:197], v[100:103]
	v_mfma_f32_16x16x32_bf16 v[96:99], v[178:181], v[194:197], v[96:99]
	v_mfma_f32_16x16x32_bf16 v[84:87], v[170:173], v[202:205], v[84:87]
	v_mfma_f32_16x16x32_bf16 v[80:83], v[178:181], v[202:205], v[80:83]
	v_mfma_f32_16x16x32_bf16 v[68:71], v[170:173], v[210:213], v[68:71]
	v_mfma_f32_16x16x32_bf16 v[64:67], v[178:181], v[210:213], v[64:67]
	v_mfma_f32_16x16x32_bf16 v[116:119], v[174:177], v[190:193], v[116:119]
	v_mfma_f32_16x16x32_bf16 v[112:115], v[182:185], v[190:193], v[112:115]
	v_mfma_f32_16x16x32_bf16 v[100:103], v[174:177], v[198:201], v[100:103]
	v_mfma_f32_16x16x32_bf16 v[96:99], v[182:185], v[198:201], v[96:99]
	v_mfma_f32_16x16x32_bf16 v[84:87], v[174:177], v[206:209], v[84:87]
	v_mfma_f32_16x16x32_bf16 v[80:83], v[182:185], v[206:209], v[80:83]
	v_mfma_f32_16x16x32_bf16 v[68:71], v[174:177], v[214:217], v[68:71]
	v_mfma_f32_16x16x32_bf16 v[64:67], v[182:185], v[214:217], v[64:67]
	s_setprio 0
	s_barrier
	s_add_i32 s72, s65, s43
	v_lshl_add_u64 v[150:151], s[36:37], 0, v[130:131]
	s_mov_b32 m0, s72
	s_nop 0
	global_load_lds_dwordx4 v[150:151], off
	s_add_i32 m0, s72, 0x2000
	s_add_u32 s72, s36, 0x40000
	v_lshl_add_u64 v[218:219], s[36:37], 0, v[134:135]
	s_addc_u32 s73, s37, 0
	s_add_i32 s74, s67, s43
	global_load_lds_dwordx4 v[218:219], off
	v_lshl_add_u64 v[220:221], s[72:73], 0, v[130:131]
	s_mov_b32 m0, s74
	v_lshl_add_u64 v[222:223], s[38:39], 0, v[132:133]
	global_load_lds_dwordx4 v[220:221], off
	v_lshl_add_u64 v[220:221], s[72:73], 0, v[134:135]
	s_add_i32 m0, s74, 0x2000
	s_nop 0
	global_load_lds_dwordx4 v[220:221], off
	v_lshl_add_u64 v[220:221], s[38:39], 0, v[128:129]
	s_mov_b32 m0, s31
	s_nop 0
	global_load_lds_dwordx4 v[220:221], off
	s_mov_b32 m0, s46
	s_nop 0
	global_load_lds_dwordx4 v[222:223], off
	ds_read_b128 v[186:189], v157 offset:16384
	ds_read_b128 v[190:193], v157 offset:17408
	ds_read_b128 v[194:197], v157 offset:18432
	ds_read_b128 v[198:201], v157 offset:19456
	ds_read_b128 v[202:205], v157 offset:20480
	ds_read_b128 v[206:209], v157 offset:21504
	ds_read_b128 v[210:213], v157 offset:22528
	ds_read_b128 v[214:217], v157 offset:23552
	s_waitcnt vmcnt(8)
	s_waitcnt lgkmcnt(0)
	s_barrier
	s_setprio 1
	s_waitcnt lgkmcnt(0)
	v_mfma_f32_16x16x32_bf16 v[60:63], v[146:149], v[186:189], v[60:63]
	v_mfma_f32_16x16x32_bf16 v[56:59], v[162:165], v[186:189], v[56:59]
	v_mfma_f32_16x16x32_bf16 v[44:47], v[146:149], v[194:197], v[44:47]
	v_mfma_f32_16x16x32_bf16 v[40:43], v[162:165], v[194:197], v[40:43]
	v_mfma_f32_16x16x32_bf16 v[28:31], v[146:149], v[202:205], v[28:31]
	v_mfma_f32_16x16x32_bf16 v[24:27], v[162:165], v[202:205], v[24:27]
	v_mfma_f32_16x16x32_bf16 v[12:15], v[146:149], v[210:213], v[12:15]
	v_mfma_f32_16x16x32_bf16 v[8:11], v[162:165], v[210:213], v[8:11]
	v_mfma_f32_16x16x32_bf16 v[60:63], v[158:161], v[190:193], v[60:63]
	v_mfma_f32_16x16x32_bf16 v[56:59], v[166:169], v[190:193], v[56:59]
	v_mfma_f32_16x16x32_bf16 v[44:47], v[158:161], v[198:201], v[44:47]
	v_mfma_f32_16x16x32_bf16 v[40:43], v[166:169], v[198:201], v[40:43]
	v_mfma_f32_16x16x32_bf16 v[28:31], v[158:161], v[206:209], v[28:31]
	v_mfma_f32_16x16x32_bf16 v[24:27], v[166:169], v[206:209], v[24:27]
	v_mfma_f32_16x16x32_bf16 v[12:15], v[158:161], v[214:217], v[12:15]
	v_mfma_f32_16x16x32_bf16 v[8:11], v[166:169], v[214:217], v[8:11]
	s_setprio 0
	s_setprio 1
	v_mfma_f32_16x16x32_bf16 v[52:55], v[170:173], v[186:189], v[52:55]
	v_mfma_f32_16x16x32_bf16 v[48:51], v[178:181], v[186:189], v[48:51]
	v_mfma_f32_16x16x32_bf16 v[36:39], v[170:173], v[194:197], v[36:39]
	v_mfma_f32_16x16x32_bf16 v[32:35], v[178:181], v[194:197], v[32:35]
	v_mfma_f32_16x16x32_bf16 v[20:23], v[170:173], v[202:205], v[20:23]
	v_mfma_f32_16x16x32_bf16 v[16:19], v[178:181], v[202:205], v[16:19]
	v_mfma_f32_16x16x32_bf16 v[4:7], v[170:173], v[210:213], v[4:7]
	v_mfma_f32_16x16x32_bf16 v[0:3], v[178:181], v[210:213], v[0:3]
	v_mfma_f32_16x16x32_bf16 v[52:55], v[174:177], v[190:193], v[52:55]
	v_mfma_f32_16x16x32_bf16 v[48:51], v[182:185], v[190:193], v[48:51]
	v_mfma_f32_16x16x32_bf16 v[36:39], v[174:177], v[198:201], v[36:39]
	v_mfma_f32_16x16x32_bf16 v[32:35], v[182:185], v[198:201], v[32:35]
	v_mfma_f32_16x16x32_bf16 v[20:23], v[174:177], v[206:209], v[20:23]
	v_mfma_f32_16x16x32_bf16 v[16:19], v[182:185], v[206:209], v[16:19]
	v_mfma_f32_16x16x32_bf16 v[4:7], v[174:177], v[214:217], v[4:7]
	v_mfma_f32_16x16x32_bf16 v[0:3], v[182:185], v[214:217], v[0:3]
	s_setprio 0
	s_barrier
	s_add_i32 s72, 0, 0x18000
	s_add_i32 s73, 0, 0x1c000
	s_add_u32 s38, s38, 0x40000
	s_addc_u32 s39, s39, 0
	s_mov_b32 m0, s47
	v_lshl_add_u64 v[224:225], s[38:39], 0, v[128:129]
	global_load_lds_dwordx4 v[224:225], off
	v_lshl_add_u64 v[224:225], s[38:39], 0, v[132:133]
	s_mov_b32 m0, s48
	s_nop 0
	global_load_lds_dwordx4 v[224:225], off
	v_add_u32_e32 v136, s72, v153
	ds_read_b128 v[146:149], v136
	ds_read_b128 v[158:161], v136 offset:1024
	ds_read_b128 v[162:165], v136 offset:2048
	ds_read_b128 v[166:169], v136 offset:3072
	v_add_u32_e32 v136, s73, v153
	ds_read_b128 v[170:173], v136
	ds_read_b128 v[174:177], v136 offset:1024
	ds_read_b128 v[178:181], v136 offset:2048
	ds_read_b128 v[182:185], v136 offset:3072
	ds_read_b128 v[186:189], v157 offset:32768
	ds_read_b128 v[190:193], v157 offset:33792
	ds_read_b128 v[194:197], v157 offset:34816
	ds_read_b128 v[198:201], v157 offset:35840
	ds_read_b128 v[202:205], v157 offset:36864
	ds_read_b128 v[206:209], v157 offset:37888
	ds_read_b128 v[210:213], v157 offset:38912
	ds_read_b128 v[214:217], v157 offset:39936
	s_waitcnt vmcnt(8)
	s_waitcnt lgkmcnt(0)
	s_barrier
	s_setprio 1
	s_waitcnt lgkmcnt(0)
	v_mfma_f32_16x16x32_bf16 v[124:127], v[146:149], v[186:189], v[124:127]
	v_mfma_f32_16x16x32_bf16 v[120:123], v[162:165], v[186:189], v[120:123]
	v_mfma_f32_16x16x32_bf16 v[108:111], v[146:149], v[194:197], v[108:111]
	v_mfma_f32_16x16x32_bf16 v[104:107], v[162:165], v[194:197], v[104:107]
	v_mfma_f32_16x16x32_bf16 v[92:95], v[146:149], v[202:205], v[92:95]
	v_mfma_f32_16x16x32_bf16 v[88:91], v[162:165], v[202:205], v[88:91]
	v_mfma_f32_16x16x32_bf16 v[76:79], v[146:149], v[210:213], v[76:79]
	v_mfma_f32_16x16x32_bf16 v[72:75], v[162:165], v[210:213], v[72:75]
	v_mfma_f32_16x16x32_bf16 v[124:127], v[158:161], v[190:193], v[124:127]
	v_mfma_f32_16x16x32_bf16 v[120:123], v[166:169], v[190:193], v[120:123]
	v_mfma_f32_16x16x32_bf16 v[108:111], v[158:161], v[198:201], v[108:111]
	v_mfma_f32_16x16x32_bf16 v[104:107], v[166:169], v[198:201], v[104:107]
	v_mfma_f32_16x16x32_bf16 v[92:95], v[158:161], v[206:209], v[92:95]
	v_mfma_f32_16x16x32_bf16 v[88:91], v[166:169], v[206:209], v[88:91]
	v_mfma_f32_16x16x32_bf16 v[76:79], v[158:161], v[214:217], v[76:79]
	v_mfma_f32_16x16x32_bf16 v[72:75], v[166:169], v[214:217], v[72:75]
	s_setprio 0
	s_setprio 1
	v_mfma_f32_16x16x32_bf16 v[116:119], v[170:173], v[186:189], v[116:119]
	v_mfma_f32_16x16x32_bf16 v[112:115], v[178:181], v[186:189], v[112:115]
	v_mfma_f32_16x16x32_bf16 v[100:103], v[170:173], v[194:197], v[100:103]
	v_mfma_f32_16x16x32_bf16 v[96:99], v[178:181], v[194:197], v[96:99]
	v_mfma_f32_16x16x32_bf16 v[84:87], v[170:173], v[202:205], v[84:87]
	v_mfma_f32_16x16x32_bf16 v[80:83], v[178:181], v[202:205], v[80:83]
	v_mfma_f32_16x16x32_bf16 v[68:71], v[170:173], v[210:213], v[68:71]
	v_mfma_f32_16x16x32_bf16 v[64:67], v[178:181], v[210:213], v[64:67]
	v_mfma_f32_16x16x32_bf16 v[116:119], v[174:177], v[190:193], v[116:119]
	v_mfma_f32_16x16x32_bf16 v[112:115], v[182:185], v[190:193], v[112:115]
	v_mfma_f32_16x16x32_bf16 v[100:103], v[174:177], v[198:201], v[100:103]
	v_mfma_f32_16x16x32_bf16 v[96:99], v[182:185], v[198:201], v[96:99]
	v_mfma_f32_16x16x32_bf16 v[84:87], v[174:177], v[206:209], v[84:87]
	v_mfma_f32_16x16x32_bf16 v[80:83], v[182:185], v[206:209], v[80:83]
	v_mfma_f32_16x16x32_bf16 v[68:71], v[174:177], v[214:217], v[68:71]
	v_mfma_f32_16x16x32_bf16 v[64:67], v[182:185], v[214:217], v[64:67]
	s_setprio 0
	s_barrier
	s_add_i32 s38, s72, s43
	v_lshl_add_u64 v[150:151], v[150:151], 0, s[12:13]
	s_mov_b32 m0, s38
	s_nop 0
	global_load_lds_dwordx4 v[150:151], off
	s_add_i32 m0, s38, 0x2000
	s_add_u32 s36, s36, 0x40080
	v_lshl_add_u64 v[150:151], v[218:219], 0, s[12:13]
	s_addc_u32 s37, s37, 0
	s_add_i32 s38, s73, s43
	global_load_lds_dwordx4 v[150:151], off
	v_lshl_add_u64 v[150:151], s[36:37], 0, v[130:131]
	s_mov_b32 m0, s38
	s_nop 0
	global_load_lds_dwordx4 v[150:151], off
	v_lshl_add_u64 v[150:151], s[36:37], 0, v[134:135]
	s_add_i32 m0, s38, 0x2000
	s_nop 0
	global_load_lds_dwordx4 v[150:151], off
	v_lshl_add_u64 v[150:151], v[220:221], 0, s[12:13]
	s_mov_b32 m0, s60
	s_nop 0
	global_load_lds_dwordx4 v[150:151], off
	v_lshl_add_u64 v[150:151], v[222:223], 0, s[12:13]
	s_mov_b32 m0, s61
	s_nop 0
	global_load_lds_dwordx4 v[150:151], off
	ds_read_b128 v[186:189], v157 offset:49152
	ds_read_b128 v[190:193], v157 offset:50176
	ds_read_b128 v[194:197], v157 offset:51200
	ds_read_b128 v[198:201], v157 offset:52224
	ds_read_b128 v[202:205], v157 offset:53248
	ds_read_b128 v[206:209], v157 offset:54272
	ds_read_b128 v[210:213], v157 offset:55296
	ds_read_b128 v[214:217], v157 offset:56320
	s_waitcnt vmcnt(8)
	s_waitcnt lgkmcnt(0)
	s_barrier
	s_setprio 1
	s_waitcnt lgkmcnt(0)
	v_mfma_f32_16x16x32_bf16 v[60:63], v[146:149], v[186:189], v[60:63]
	v_mfma_f32_16x16x32_bf16 v[56:59], v[162:165], v[186:189], v[56:59]
	v_mfma_f32_16x16x32_bf16 v[44:47], v[146:149], v[194:197], v[44:47]
	v_mfma_f32_16x16x32_bf16 v[40:43], v[162:165], v[194:197], v[40:43]
	v_mfma_f32_16x16x32_bf16 v[28:31], v[146:149], v[202:205], v[28:31]
	v_mfma_f32_16x16x32_bf16 v[24:27], v[162:165], v[202:205], v[24:27]
	v_mfma_f32_16x16x32_bf16 v[12:15], v[146:149], v[210:213], v[12:15]
	v_mfma_f32_16x16x32_bf16 v[8:11], v[162:165], v[210:213], v[8:11]
	v_mfma_f32_16x16x32_bf16 v[60:63], v[158:161], v[190:193], v[60:63]
	v_mfma_f32_16x16x32_bf16 v[56:59], v[166:169], v[190:193], v[56:59]
	v_mfma_f32_16x16x32_bf16 v[44:47], v[158:161], v[198:201], v[44:47]
	v_mfma_f32_16x16x32_bf16 v[40:43], v[166:169], v[198:201], v[40:43]
	v_mfma_f32_16x16x32_bf16 v[28:31], v[158:161], v[206:209], v[28:31]
	v_mfma_f32_16x16x32_bf16 v[24:27], v[166:169], v[206:209], v[24:27]
	v_mfma_f32_16x16x32_bf16 v[12:15], v[158:161], v[214:217], v[12:15]
	v_mfma_f32_16x16x32_bf16 v[8:11], v[166:169], v[214:217], v[8:11]
	s_setprio 0
	s_setprio 1
	v_mfma_f32_16x16x32_bf16 v[52:55], v[170:173], v[186:189], v[52:55]
	v_mfma_f32_16x16x32_bf16 v[48:51], v[178:181], v[186:189], v[48:51]
	v_mfma_f32_16x16x32_bf16 v[36:39], v[170:173], v[194:197], v[36:39]
	v_mfma_f32_16x16x32_bf16 v[32:35], v[178:181], v[194:197], v[32:35]
	v_mfma_f32_16x16x32_bf16 v[20:23], v[170:173], v[202:205], v[20:23]
	v_mfma_f32_16x16x32_bf16 v[16:19], v[178:181], v[202:205], v[16:19]
	v_mfma_f32_16x16x32_bf16 v[4:7], v[170:173], v[210:213], v[4:7]
	v_mfma_f32_16x16x32_bf16 v[0:3], v[178:181], v[210:213], v[0:3]
	v_mfma_f32_16x16x32_bf16 v[52:55], v[174:177], v[190:193], v[52:55]
	v_mfma_f32_16x16x32_bf16 v[48:51], v[182:185], v[190:193], v[48:51]
	v_mfma_f32_16x16x32_bf16 v[36:39], v[174:177], v[198:201], v[36:39]
	v_mfma_f32_16x16x32_bf16 v[32:35], v[182:185], v[198:201], v[32:35]
	v_mfma_f32_16x16x32_bf16 v[20:23], v[174:177], v[206:209], v[20:23]
	v_mfma_f32_16x16x32_bf16 v[16:19], v[182:185], v[206:209], v[16:19]
	v_mfma_f32_16x16x32_bf16 v[4:7], v[174:177], v[214:217], v[4:7]
	v_mfma_f32_16x16x32_bf16 v[0:3], v[182:185], v[214:217], v[0:3]
	s_setprio 0
	s_barrier
	s_add_i32 s71, s71, 2
	s_add_u32 s34, s34, 0x100
	s_addc_u32 s35, s35, 0
	s_add_u32 s69, s69, 0x100
	s_addc_u32 s70, s70, 0
	s_cmp_gt_u32 s71, 13
	s_cbranch_scc0 .LBB0_217
	s_and_b64 vcc, exec, s[14:15]
	s_cbranch_vccz .LBB0_220
	s_barrier

.LBB0_471:
	s_add_u32 s34, s30, 0xfffc0080
	s_addc_u32 s35, s31, -1
	s_cmp_eq_u32 s69, 12
	s_cselect_b32 s37, s21, s35
	s_cselect_b32 s36, s27, s34
	s_cselect_b32 s35, s19, s68
	s_cselect_b32 s34, s64, s65
	v_lshl_add_u64 v[214:215], s[30:31], 0, v[184:185]
	s_add_i32 m0, s29, 0xc000
	s_nop 0
	global_load_lds_dwordx4 v[214:215], off
	v_lshl_add_u64 v[214:215], s[30:31], 0, v[186:187]
	s_add_i32 m0, s29, 0xe000
	s_nop 0
	global_load_lds_dwordx4 v[214:215], off
	ds_read_b128 v[128:131], v207
	ds_read_b128 v[132:135], v207 offset:1024
	ds_read_b128 v[136:139], v207 offset:2048
	ds_read_b128 v[140:143], v207 offset:3072
	ds_read_b128 v[144:147], v208
	ds_read_b128 v[148:151], v208 offset:1024
	ds_read_b128 v[152:155], v208 offset:2048
	ds_read_b128 v[156:159], v208 offset:3072
	ds_read_b128 v[160:163], v209
	ds_read_b128 v[164:167], v209 offset:1024
	ds_read_b128 v[168:171], v209 offset:2048
	ds_read_b128 v[172:175], v209 offset:3072
	ds_read_b128 v[192:195], v209 offset:4096
	ds_read_b128 v[196:199], v209 offset:5120
	ds_read_b128 v[200:203], v209 offset:6144
	ds_read_b128 v[210:213], v209 offset:7168
	s_waitcnt vmcnt(8)
	s_waitcnt lgkmcnt(0)
	s_barrier
	s_setprio 1
	s_waitcnt lgkmcnt(0)
	v_mfma_f32_16x16x32_bf16 v[124:127], v[128:131], v[160:163], v[124:127]
	v_mfma_f32_16x16x32_bf16 v[120:123], v[136:139], v[160:163], v[120:123]
	v_mfma_f32_16x16x32_bf16 v[108:111], v[128:131], v[168:171], v[108:111]
	v_mfma_f32_16x16x32_bf16 v[104:107], v[136:139], v[168:171], v[104:107]
	v_mfma_f32_16x16x32_bf16 v[92:95], v[128:131], v[192:195], v[92:95]
	v_mfma_f32_16x16x32_bf16 v[88:91], v[136:139], v[192:195], v[88:91]
	v_mfma_f32_16x16x32_bf16 v[76:79], v[128:131], v[200:203], v[76:79]
	v_mfma_f32_16x16x32_bf16 v[72:75], v[136:139], v[200:203], v[72:75]
	v_mfma_f32_16x16x32_bf16 v[124:127], v[132:135], v[164:167], v[124:127]
	v_mfma_f32_16x16x32_bf16 v[120:123], v[140:143], v[164:167], v[120:123]
	v_mfma_f32_16x16x32_bf16 v[108:111], v[132:135], v[172:175], v[108:111]
	v_mfma_f32_16x16x32_bf16 v[104:107], v[140:143], v[172:175], v[104:107]
	v_mfma_f32_16x16x32_bf16 v[92:95], v[132:135], v[196:199], v[92:95]
	v_mfma_f32_16x16x32_bf16 v[88:91], v[140:143], v[196:199], v[88:91]
	v_mfma_f32_16x16x32_bf16 v[76:79], v[132:135], v[210:213], v[76:79]
	v_mfma_f32_16x16x32_bf16 v[72:75], v[140:143], v[210:213], v[72:75]
	s_setprio 0
	s_setprio 1
	v_mfma_f32_16x16x32_bf16 v[116:119], v[144:147], v[160:163], v[116:119]
	v_mfma_f32_16x16x32_bf16 v[112:115], v[152:155], v[160:163], v[112:115]
	v_mfma_f32_16x16x32_bf16 v[100:103], v[144:147], v[168:171], v[100:103]
	v_mfma_f32_16x16x32_bf16 v[96:99], v[152:155], v[168:171], v[96:99]
	v_mfma_f32_16x16x32_bf16 v[84:87], v[144:147], v[192:195], v[84:87]
	v_mfma_f32_16x16x32_bf16 v[80:83], v[152:155], v[192:195], v[80:83]
	v_mfma_f32_16x16x32_bf16 v[68:71], v[144:147], v[200:203], v[68:71]
	v_mfma_f32_16x16x32_bf16 v[64:67], v[152:155], v[200:203], v[64:67]
	v_mfma_f32_16x16x32_bf16 v[116:119], v[148:151], v[164:167], v[116:119]
	v_mfma_f32_16x16x32_bf16 v[112:115], v[156:159], v[164:167], v[112:115]
	v_mfma_f32_16x16x32_bf16 v[100:103], v[148:151], v[172:175], v[100:103]
	v_mfma_f32_16x16x32_bf16 v[96:99], v[156:159], v[172:175], v[96:99]
	v_mfma_f32_16x16x32_bf16 v[84:87], v[148:151], v[196:199], v[84:87]
	v_mfma_f32_16x16x32_bf16 v[80:83], v[156:159], v[196:199], v[80:83]
	v_mfma_f32_16x16x32_bf16 v[68:71], v[148:151], v[210:213], v[68:71]
	v_mfma_f32_16x16x32_bf16 v[64:67], v[156:159], v[210:213], v[64:67]
	s_setprio 0
	s_barrier
	s_add_i32 s70, s62, s40
	v_lshl_add_u64 v[214:215], s[34:35], 0, v[178:179]
	s_mov_b32 m0, s70
	s_nop 0
	global_load_lds_dwordx4 v[214:215], off
	s_add_i32 m0, s70, 0x2000
	s_add_u32 s70, s34, 0x40000
	v_lshl_add_u64 v[216:217], s[34:35], 0, v[182:183]
	s_addc_u32 s71, s35, 0
	s_add_i32 s72, s63, s40
	global_load_lds_dwordx4 v[216:217], off
	v_lshl_add_u64 v[218:219], s[70:71], 0, v[178:179]
	s_mov_b32 m0, s72
	v_lshl_add_u64 v[220:221], s[36:37], 0, v[180:181]
	global_load_lds_dwordx4 v[218:219], off
	v_lshl_add_u64 v[218:219], s[70:71], 0, v[182:183]
	s_add_i32 m0, s72, 0x2000
	s_nop 0
	global_load_lds_dwordx4 v[218:219], off
	v_lshl_add_u64 v[218:219], s[36:37], 0, v[176:177]
	s_mov_b32 m0, s29
	s_nop 0
	global_load_lds_dwordx4 v[218:219], off
	s_mov_b32 m0, s41
	s_nop 0
	global_load_lds_dwordx4 v[220:221], off
	ds_read_b128 v[160:163], v209 offset:16384
	ds_read_b128 v[164:167], v209 offset:17408
	ds_read_b128 v[168:171], v209 offset:18432
	ds_read_b128 v[172:175], v209 offset:19456
	ds_read_b128 v[192:195], v209 offset:20480
	ds_read_b128 v[196:199], v209 offset:21504
	ds_read_b128 v[200:203], v209 offset:22528
	ds_read_b128 v[210:213], v209 offset:23552
	s_waitcnt vmcnt(8)
	s_waitcnt lgkmcnt(0)
	s_barrier
	s_setprio 1
	s_waitcnt lgkmcnt(0)
	v_mfma_f32_16x16x32_bf16 v[60:63], v[128:131], v[160:163], v[60:63]
	v_mfma_f32_16x16x32_bf16 v[56:59], v[136:139], v[160:163], v[56:59]
	v_mfma_f32_16x16x32_bf16 v[44:47], v[128:131], v[168:171], v[44:47]
	v_mfma_f32_16x16x32_bf16 v[40:43], v[136:139], v[168:171], v[40:43]
	v_mfma_f32_16x16x32_bf16 v[28:31], v[128:131], v[192:195], v[28:31]
	v_mfma_f32_16x16x32_bf16 v[24:27], v[136:139], v[192:195], v[24:27]
	v_mfma_f32_16x16x32_bf16 v[12:15], v[128:131], v[200:203], v[12:15]
	v_mfma_f32_16x16x32_bf16 v[8:11], v[136:139], v[200:203], v[8:11]
	v_mfma_f32_16x16x32_bf16 v[60:63], v[132:135], v[164:167], v[60:63]
	v_mfma_f32_16x16x32_bf16 v[56:59], v[140:143], v[164:167], v[56:59]
	v_mfma_f32_16x16x32_bf16 v[44:47], v[132:135], v[172:175], v[44:47]
	v_mfma_f32_16x16x32_bf16 v[40:43], v[140:143], v[172:175], v[40:43]
	v_mfma_f32_16x16x32_bf16 v[28:31], v[132:135], v[196:199], v[28:31]
	v_mfma_f32_16x16x32_bf16 v[24:27], v[140:143], v[196:199], v[24:27]
	v_mfma_f32_16x16x32_bf16 v[12:15], v[132:135], v[210:213], v[12:15]
	v_mfma_f32_16x16x32_bf16 v[8:11], v[140:143], v[210:213], v[8:11]
	s_setprio 0
	s_setprio 1
	v_mfma_f32_16x16x32_bf16 v[52:55], v[144:147], v[160:163], v[52:55]
	v_mfma_f32_16x16x32_bf16 v[48:51], v[152:155], v[160:163], v[48:51]
	v_mfma_f32_16x16x32_bf16 v[36:39], v[144:147], v[168:171], v[36:39]
	v_mfma_f32_16x16x32_bf16 v[32:35], v[152:155], v[168:171], v[32:35]
	v_mfma_f32_16x16x32_bf16 v[20:23], v[144:147], v[192:195], v[20:23]
	v_mfma_f32_16x16x32_bf16 v[16:19], v[152:155], v[192:195], v[16:19]
	v_mfma_f32_16x16x32_bf16 v[4:7], v[144:147], v[200:203], v[4:7]
	v_mfma_f32_16x16x32_bf16 v[0:3], v[152:155], v[200:203], v[0:3]
	v_mfma_f32_16x16x32_bf16 v[52:55], v[148:151], v[164:167], v[52:55]
	v_mfma_f32_16x16x32_bf16 v[48:51], v[156:159], v[164:167], v[48:51]
	v_mfma_f32_16x16x32_bf16 v[36:39], v[148:151], v[172:175], v[36:39]
	v_mfma_f32_16x16x32_bf16 v[32:35], v[156:159], v[172:175], v[32:35]
	v_mfma_f32_16x16x32_bf16 v[20:23], v[148:151], v[196:199], v[20:23]
	v_mfma_f32_16x16x32_bf16 v[16:19], v[156:159], v[196:199], v[16:19]
	v_mfma_f32_16x16x32_bf16 v[4:7], v[148:151], v[210:213], v[4:7]
	v_mfma_f32_16x16x32_bf16 v[0:3], v[156:159], v[210:213], v[0:3]
	s_setprio 0
	s_barrier
	s_add_i32 s70, 0, 0x18000
	s_add_i32 s71, 0, 0x1c000
	s_add_u32 s36, s36, 0x40000
	s_addc_u32 s37, s37, 0
	s_mov_b32 m0, s42
	v_lshl_add_u64 v[222:223], s[36:37], 0, v[176:177]
	global_load_lds_dwordx4 v[222:223], off
	v_lshl_add_u64 v[222:223], s[36:37], 0, v[180:181]
	s_mov_b32 m0, s43
	s_nop 0
	global_load_lds_dwordx4 v[222:223], off
	v_add_u32_e32 v140, s70, v206
	v_add_u32_e32 v156, s71, v206
	ds_read_b128 v[128:131], v140
	ds_read_b128 v[132:135], v140 offset:1024
	ds_read_b128 v[136:139], v140 offset:2048
	ds_read_b128 v[140:143], v140 offset:3072
	ds_read_b128 v[144:147], v156
	ds_read_b128 v[148:151], v156 offset:1024
	ds_read_b128 v[152:155], v156 offset:2048
	ds_read_b128 v[156:159], v156 offset:3072
	ds_read_b128 v[160:163], v209 offset:32768
	ds_read_b128 v[164:167], v209 offset:33792
	ds_read_b128 v[168:171], v209 offset:34816
	ds_read_b128 v[172:175], v209 offset:35840
	ds_read_b128 v[192:195], v209 offset:36864
	ds_read_b128 v[196:199], v209 offset:37888
	ds_read_b128 v[200:203], v209 offset:38912
	ds_read_b128 v[210:213], v209 offset:39936
	s_waitcnt vmcnt(8)
	s_waitcnt lgkmcnt(0)
	s_barrier
	s_setprio 1
	s_waitcnt lgkmcnt(0)
	v_mfma_f32_16x16x32_bf16 v[124:127], v[128:131], v[160:163], v[124:127]
	v_mfma_f32_16x16x32_bf16 v[120:123], v[136:139], v[160:163], v[120:123]
	v_mfma_f32_16x16x32_bf16 v[108:111], v[128:131], v[168:171], v[108:111]
	v_mfma_f32_16x16x32_bf16 v[104:107], v[136:139], v[168:171], v[104:107]
	v_mfma_f32_16x16x32_bf16 v[92:95], v[128:131], v[192:195], v[92:95]
	v_mfma_f32_16x16x32_bf16 v[88:91], v[136:139], v[192:195], v[88:91]
	v_mfma_f32_16x16x32_bf16 v[76:79], v[128:131], v[200:203], v[76:79]
	v_mfma_f32_16x16x32_bf16 v[72:75], v[136:139], v[200:203], v[72:75]
	v_mfma_f32_16x16x32_bf16 v[124:127], v[132:135], v[164:167], v[124:127]
	v_mfma_f32_16x16x32_bf16 v[120:123], v[140:143], v[164:167], v[120:123]
	v_mfma_f32_16x16x32_bf16 v[108:111], v[132:135], v[172:175], v[108:111]
	v_mfma_f32_16x16x32_bf16 v[104:107], v[140:143], v[172:175], v[104:107]
	v_mfma_f32_16x16x32_bf16 v[92:95], v[132:135], v[196:199], v[92:95]
	v_mfma_f32_16x16x32_bf16 v[88:91], v[140:143], v[196:199], v[88:91]
	v_mfma_f32_16x16x32_bf16 v[76:79], v[132:135], v[210:213], v[76:79]
	v_mfma_f32_16x16x32_bf16 v[72:75], v[140:143], v[210:213], v[72:75]
	s_setprio 0
	s_setprio 1
	v_mfma_f32_16x16x32_bf16 v[116:119], v[144:147], v[160:163], v[116:119]
	v_mfma_f32_16x16x32_bf16 v[112:115], v[152:155], v[160:163], v[112:115]
	v_mfma_f32_16x16x32_bf16 v[100:103], v[144:147], v[168:171], v[100:103]
	v_mfma_f32_16x16x32_bf16 v[96:99], v[152:155], v[168:171], v[96:99]
	v_mfma_f32_16x16x32_bf16 v[84:87], v[144:147], v[192:195], v[84:87]
	v_mfma_f32_16x16x32_bf16 v[80:83], v[152:155], v[192:195], v[80:83]
	v_mfma_f32_16x16x32_bf16 v[68:71], v[144:147], v[200:203], v[68:71]
	v_mfma_f32_16x16x32_bf16 v[64:67], v[152:155], v[200:203], v[64:67]
	v_mfma_f32_16x16x32_bf16 v[116:119], v[148:151], v[164:167], v[116:119]
	v_mfma_f32_16x16x32_bf16 v[112:115], v[156:159], v[164:167], v[112:115]
	v_mfma_f32_16x16x32_bf16 v[100:103], v[148:151], v[172:175], v[100:103]
	v_mfma_f32_16x16x32_bf16 v[96:99], v[156:159], v[172:175], v[96:99]
	v_mfma_f32_16x16x32_bf16 v[84:87], v[148:151], v[196:199], v[84:87]
	v_mfma_f32_16x16x32_bf16 v[80:83], v[156:159], v[196:199], v[80:83]
	v_mfma_f32_16x16x32_bf16 v[68:71], v[148:151], v[210:213], v[68:71]
	v_mfma_f32_16x16x32_bf16 v[64:67], v[156:159], v[210:213], v[64:67]
	s_setprio 0
	s_barrier
	s_add_i32 s36, s70, s40
	v_lshl_add_u64 v[214:215], v[214:215], 0, s[14:15]
	s_mov_b32 m0, s36
	s_nop 0
	global_load_lds_dwordx4 v[214:215], off
	s_add_i32 m0, s36, 0x2000
	s_add_u32 s34, s34, 0x40080
	v_lshl_add_u64 v[214:215], v[216:217], 0, s[14:15]
	s_addc_u32 s35, s35, 0
	s_add_i32 s36, s71, s40
	global_load_lds_dwordx4 v[214:215], off
	v_lshl_add_u64 v[214:215], s[34:35], 0, v[178:179]
	s_mov_b32 m0, s36
	s_nop 0
	global_load_lds_dwordx4 v[214:215], off
	v_lshl_add_u64 v[214:215], s[34:35], 0, v[182:183]
	s_add_i32 m0, s36, 0x2000
	s_nop 0
	global_load_lds_dwordx4 v[214:215], off
	v_lshl_add_u64 v[214:215], v[218:219], 0, s[14:15]
	s_mov_b32 m0, s49
	s_nop 0
	global_load_lds_dwordx4 v[214:215], off
	v_lshl_add_u64 v[214:215], v[220:221], 0, s[14:15]
	s_mov_b32 m0, s50
	s_nop 0
	global_load_lds_dwordx4 v[214:215], off
	ds_read_b128 v[160:163], v209 offset:49152
	ds_read_b128 v[164:167], v209 offset:50176
	ds_read_b128 v[168:171], v209 offset:51200
	ds_read_b128 v[172:175], v209 offset:52224
	ds_read_b128 v[192:195], v209 offset:53248
	ds_read_b128 v[196:199], v209 offset:54272
	ds_read_b128 v[200:203], v209 offset:55296
	ds_read_b128 v[210:213], v209 offset:56320
	s_waitcnt vmcnt(8)
	s_waitcnt lgkmcnt(0)
	s_barrier
	s_setprio 1
	s_waitcnt lgkmcnt(0)
	v_mfma_f32_16x16x32_bf16 v[60:63], v[128:131], v[160:163], v[60:63]
	v_mfma_f32_16x16x32_bf16 v[56:59], v[136:139], v[160:163], v[56:59]
	v_mfma_f32_16x16x32_bf16 v[44:47], v[128:131], v[168:171], v[44:47]
	v_mfma_f32_16x16x32_bf16 v[40:43], v[136:139], v[168:171], v[40:43]
	v_mfma_f32_16x16x32_bf16 v[28:31], v[128:131], v[192:195], v[28:31]
	v_mfma_f32_16x16x32_bf16 v[24:27], v[136:139], v[192:195], v[24:27]
	v_mfma_f32_16x16x32_bf16 v[12:15], v[128:131], v[200:203], v[12:15]
	v_mfma_f32_16x16x32_bf16 v[8:11], v[136:139], v[200:203], v[8:11]
	v_mfma_f32_16x16x32_bf16 v[60:63], v[132:135], v[164:167], v[60:63]
	v_mfma_f32_16x16x32_bf16 v[56:59], v[140:143], v[164:167], v[56:59]
	v_mfma_f32_16x16x32_bf16 v[44:47], v[132:135], v[172:175], v[44:47]
	v_mfma_f32_16x16x32_bf16 v[40:43], v[140:143], v[172:175], v[40:43]
	v_mfma_f32_16x16x32_bf16 v[28:31], v[132:135], v[196:199], v[28:31]
	v_mfma_f32_16x16x32_bf16 v[24:27], v[140:143], v[196:199], v[24:27]
	v_mfma_f32_16x16x32_bf16 v[12:15], v[132:135], v[210:213], v[12:15]
	v_mfma_f32_16x16x32_bf16 v[8:11], v[140:143], v[210:213], v[8:11]
	s_setprio 0
	s_setprio 1
	v_mfma_f32_16x16x32_bf16 v[52:55], v[144:147], v[160:163], v[52:55]
	v_mfma_f32_16x16x32_bf16 v[48:51], v[152:155], v[160:163], v[48:51]
	v_mfma_f32_16x16x32_bf16 v[36:39], v[144:147], v[168:171], v[36:39]
	v_mfma_f32_16x16x32_bf16 v[32:35], v[152:155], v[168:171], v[32:35]
	v_mfma_f32_16x16x32_bf16 v[20:23], v[144:147], v[192:195], v[20:23]
	v_mfma_f32_16x16x32_bf16 v[16:19], v[152:155], v[192:195], v[16:19]
	v_mfma_f32_16x16x32_bf16 v[4:7], v[144:147], v[200:203], v[4:7]
	v_mfma_f32_16x16x32_bf16 v[0:3], v[152:155], v[200:203], v[0:3]
	v_mfma_f32_16x16x32_bf16 v[52:55], v[148:151], v[164:167], v[52:55]
	v_mfma_f32_16x16x32_bf16 v[48:51], v[156:159], v[164:167], v[48:51]
	v_mfma_f32_16x16x32_bf16 v[36:39], v[148:151], v[172:175], v[36:39]
	v_mfma_f32_16x16x32_bf16 v[32:35], v[156:159], v[172:175], v[32:35]
	v_mfma_f32_16x16x32_bf16 v[20:23], v[148:151], v[196:199], v[20:23]
	v_mfma_f32_16x16x32_bf16 v[16:19], v[156:159], v[196:199], v[16:19]
	v_mfma_f32_16x16x32_bf16 v[4:7], v[148:151], v[210:213], v[4:7]
	v_mfma_f32_16x16x32_bf16 v[0:3], v[156:159], v[210:213], v[0:3]
	s_setprio 0
	s_barrier
	s_add_i32 s69, s69, 2
	s_add_u32 s30, s30, 0x100
	s_addc_u32 s31, s31, 0
	s_add_u32 s65, s65, 0x100
	s_addc_u32 s68, s68, 0
	s_cmp_gt_u32 s69, 13
	s_cbranch_scc0 .LBB0_471
	s_and_b64 vcc, exec, s[16:17]
	s_cbranch_vccz .LBB0_474
	s_barrier

.LBB0_555:
	s_add_u32 s30, s28, 0xfffc0080
	s_addc_u32 s31, s29, -1
	s_cmp_eq_u32 s63, 12
	s_cselect_b32 s35, s19, s31
	s_cselect_b32 s34, s51, s30
	s_cselect_b32 s31, s17, s62
	s_cselect_b32 s30, s60, s61
	v_lshl_add_u64 v[144:145], s[28:29], 0, v[136:137]
	s_add_i32 m0, s25, 0xc000
	s_nop 0
	global_load_lds_dwordx4 v[144:145], off
	v_lshl_add_u64 v[144:145], s[28:29], 0, v[138:139]
	s_add_i32 m0, s25, 0xe000
	s_nop 0
	global_load_lds_dwordx4 v[144:145], off
	ds_read_b128 v[154:157], v149
	ds_read_b128 v[158:161], v149 offset:1024
	ds_read_b128 v[162:165], v149 offset:2048
	ds_read_b128 v[166:169], v149 offset:3072
	ds_read_b128 v[170:173], v150
	ds_read_b128 v[174:177], v150 offset:1024
	ds_read_b128 v[178:181], v150 offset:2048
	ds_read_b128 v[182:185], v150 offset:3072
	ds_read_b128 v[186:189], v151
	ds_read_b128 v[190:193], v151 offset:1024
	ds_read_b128 v[194:197], v151 offset:2048
	ds_read_b128 v[198:201], v151 offset:3072
	ds_read_b128 v[202:205], v151 offset:4096
	ds_read_b128 v[206:209], v151 offset:5120
	ds_read_b128 v[210:213], v151 offset:6144
	ds_read_b128 v[214:217], v151 offset:7168
	s_waitcnt vmcnt(8)
	s_waitcnt lgkmcnt(0)
	s_barrier
	s_setprio 1
	s_waitcnt lgkmcnt(0)
	v_mfma_f32_16x16x32_bf16 v[116:119], v[154:157], v[186:189], v[116:119]
	v_mfma_f32_16x16x32_bf16 v[112:115], v[162:165], v[186:189], v[112:115]
	v_mfma_f32_16x16x32_bf16 v[108:111], v[154:157], v[194:197], v[108:111]
	v_mfma_f32_16x16x32_bf16 v[100:103], v[162:165], v[194:197], v[100:103]
	v_mfma_f32_16x16x32_bf16 v[92:95], v[154:157], v[202:205], v[92:95]
	v_mfma_f32_16x16x32_bf16 v[84:87], v[162:165], v[202:205], v[84:87]
	v_mfma_f32_16x16x32_bf16 v[76:79], v[154:157], v[210:213], v[76:79]
	v_mfma_f32_16x16x32_bf16 v[68:71], v[162:165], v[210:213], v[68:71]
	v_mfma_f32_16x16x32_bf16 v[116:119], v[158:161], v[190:193], v[116:119]
	v_mfma_f32_16x16x32_bf16 v[112:115], v[166:169], v[190:193], v[112:115]
	v_mfma_f32_16x16x32_bf16 v[108:111], v[158:161], v[198:201], v[108:111]
	v_mfma_f32_16x16x32_bf16 v[100:103], v[166:169], v[198:201], v[100:103]
	v_mfma_f32_16x16x32_bf16 v[92:95], v[158:161], v[206:209], v[92:95]
	v_mfma_f32_16x16x32_bf16 v[84:87], v[166:169], v[206:209], v[84:87]
	v_mfma_f32_16x16x32_bf16 v[76:79], v[158:161], v[214:217], v[76:79]
	v_mfma_f32_16x16x32_bf16 v[68:71], v[166:169], v[214:217], v[68:71]
	s_setprio 0
	s_setprio 1
	v_mfma_f32_16x16x32_bf16 v[124:127], v[170:173], v[186:189], v[124:127]
	v_mfma_f32_16x16x32_bf16 v[120:123], v[178:181], v[186:189], v[120:123]
	v_mfma_f32_16x16x32_bf16 v[104:107], v[170:173], v[194:197], v[104:107]
	v_mfma_f32_16x16x32_bf16 v[96:99], v[178:181], v[194:197], v[96:99]
	v_mfma_f32_16x16x32_bf16 v[88:91], v[170:173], v[202:205], v[88:91]
	v_mfma_f32_16x16x32_bf16 v[80:83], v[178:181], v[202:205], v[80:83]
	v_mfma_f32_16x16x32_bf16 v[72:75], v[170:173], v[210:213], v[72:75]
	v_mfma_f32_16x16x32_bf16 v[64:67], v[178:181], v[210:213], v[64:67]
	v_mfma_f32_16x16x32_bf16 v[124:127], v[174:177], v[190:193], v[124:127]
	v_mfma_f32_16x16x32_bf16 v[120:123], v[182:185], v[190:193], v[120:123]
	v_mfma_f32_16x16x32_bf16 v[104:107], v[174:177], v[198:201], v[104:107]
	v_mfma_f32_16x16x32_bf16 v[96:99], v[182:185], v[198:201], v[96:99]
	v_mfma_f32_16x16x32_bf16 v[88:91], v[174:177], v[206:209], v[88:91]
	v_mfma_f32_16x16x32_bf16 v[80:83], v[182:185], v[206:209], v[80:83]
	v_mfma_f32_16x16x32_bf16 v[72:75], v[174:177], v[214:217], v[72:75]
	v_mfma_f32_16x16x32_bf16 v[64:67], v[182:185], v[214:217], v[64:67]
	s_setprio 0
	s_barrier
	s_add_i32 s64, s48, s36
	v_lshl_add_u64 v[144:145], s[30:31], 0, v[132:133]
	s_mov_b32 m0, s64
	s_nop 0
	global_load_lds_dwordx4 v[144:145], off
	s_add_i32 m0, s64, 0x2000
	s_add_u32 s64, s30, 0x40000
	v_lshl_add_u64 v[218:219], s[30:31], 0, v[128:129]
	s_addc_u32 s65, s31, 0
	s_add_i32 s68, s49, s36
	global_load_lds_dwordx4 v[218:219], off
	v_lshl_add_u64 v[220:221], s[64:65], 0, v[132:133]
	s_mov_b32 m0, s68
	v_lshl_add_u64 v[222:223], s[34:35], 0, v[130:131]
	global_load_lds_dwordx4 v[220:221], off
	v_lshl_add_u64 v[220:221], s[64:65], 0, v[128:129]
	s_add_i32 m0, s68, 0x2000
	s_nop 0
	global_load_lds_dwordx4 v[220:221], off
	v_lshl_add_u64 v[220:221], s[34:35], 0, v[134:135]
	s_mov_b32 m0, s25
	s_nop 0
	global_load_lds_dwordx4 v[220:221], off
	s_mov_b32 m0, s27
	s_nop 0
	global_load_lds_dwordx4 v[222:223], off
	ds_read_b128 v[186:189], v151 offset:16384
	ds_read_b128 v[190:193], v151 offset:17408
	ds_read_b128 v[194:197], v151 offset:18432
	ds_read_b128 v[198:201], v151 offset:19456
	ds_read_b128 v[202:205], v151 offset:20480
	ds_read_b128 v[206:209], v151 offset:21504
	ds_read_b128 v[210:213], v151 offset:22528
	ds_read_b128 v[214:217], v151 offset:23552
	s_waitcnt vmcnt(8)
	s_waitcnt lgkmcnt(0)
	s_barrier
	s_setprio 1
	s_waitcnt lgkmcnt(0)
	v_mfma_f32_16x16x32_bf16 v[60:63], v[154:157], v[186:189], v[60:63]
	v_mfma_f32_16x16x32_bf16 v[52:55], v[162:165], v[186:189], v[52:55]
	v_mfma_f32_16x16x32_bf16 v[44:47], v[154:157], v[194:197], v[44:47]
	v_mfma_f32_16x16x32_bf16 v[36:39], v[162:165], v[194:197], v[36:39]
	v_mfma_f32_16x16x32_bf16 v[28:31], v[154:157], v[202:205], v[28:31]
	v_mfma_f32_16x16x32_bf16 v[20:23], v[162:165], v[202:205], v[20:23]
	v_mfma_f32_16x16x32_bf16 v[12:15], v[154:157], v[210:213], v[12:15]
	v_mfma_f32_16x16x32_bf16 v[4:7], v[162:165], v[210:213], v[4:7]
	v_mfma_f32_16x16x32_bf16 v[60:63], v[158:161], v[190:193], v[60:63]
	v_mfma_f32_16x16x32_bf16 v[52:55], v[166:169], v[190:193], v[52:55]
	v_mfma_f32_16x16x32_bf16 v[44:47], v[158:161], v[198:201], v[44:47]
	v_mfma_f32_16x16x32_bf16 v[36:39], v[166:169], v[198:201], v[36:39]
	v_mfma_f32_16x16x32_bf16 v[28:31], v[158:161], v[206:209], v[28:31]
	v_mfma_f32_16x16x32_bf16 v[20:23], v[166:169], v[206:209], v[20:23]
	v_mfma_f32_16x16x32_bf16 v[12:15], v[158:161], v[214:217], v[12:15]
	v_mfma_f32_16x16x32_bf16 v[4:7], v[166:169], v[214:217], v[4:7]
	s_setprio 0
	s_setprio 1
	v_mfma_f32_16x16x32_bf16 v[56:59], v[170:173], v[186:189], v[56:59]
	v_mfma_f32_16x16x32_bf16 v[48:51], v[178:181], v[186:189], v[48:51]
	v_mfma_f32_16x16x32_bf16 v[40:43], v[170:173], v[194:197], v[40:43]
	v_mfma_f32_16x16x32_bf16 v[32:35], v[178:181], v[194:197], v[32:35]
	v_mfma_f32_16x16x32_bf16 v[24:27], v[170:173], v[202:205], v[24:27]
	v_mfma_f32_16x16x32_bf16 v[16:19], v[178:181], v[202:205], v[16:19]
	v_mfma_f32_16x16x32_bf16 v[8:11], v[170:173], v[210:213], v[8:11]
	v_mfma_f32_16x16x32_bf16 v[0:3], v[178:181], v[210:213], v[0:3]
	v_mfma_f32_16x16x32_bf16 v[56:59], v[174:177], v[190:193], v[56:59]
	v_mfma_f32_16x16x32_bf16 v[48:51], v[182:185], v[190:193], v[48:51]
	v_mfma_f32_16x16x32_bf16 v[40:43], v[174:177], v[198:201], v[40:43]
	v_mfma_f32_16x16x32_bf16 v[32:35], v[182:185], v[198:201], v[32:35]
	v_mfma_f32_16x16x32_bf16 v[24:27], v[174:177], v[206:209], v[24:27]
	v_mfma_f32_16x16x32_bf16 v[16:19], v[182:185], v[206:209], v[16:19]
	v_mfma_f32_16x16x32_bf16 v[8:11], v[174:177], v[214:217], v[8:11]
	v_mfma_f32_16x16x32_bf16 v[0:3], v[182:185], v[214:217], v[0:3]
	s_setprio 0
	s_barrier
	s_add_i32 s64, 0, 0x18000
	s_add_i32 s65, 0, 0x1c000
	s_add_u32 s34, s34, 0x40000
	s_addc_u32 s35, s35, 0
	s_mov_b32 m0, s39
	v_lshl_add_u64 v[224:225], s[34:35], 0, v[134:135]
	global_load_lds_dwordx4 v[224:225], off
	v_lshl_add_u64 v[224:225], s[34:35], 0, v[130:131]
	s_mov_b32 m0, s40
	s_nop 0
	global_load_lds_dwordx4 v[224:225], off
	v_add_u32_e32 v153, s64, v147
	ds_read_b128 v[154:157], v153
	ds_read_b128 v[158:161], v153 offset:1024
	ds_read_b128 v[162:165], v153 offset:2048
	ds_read_b128 v[166:169], v153 offset:3072
	v_add_u32_e32 v153, s65, v147
	ds_read_b128 v[170:173], v153
	ds_read_b128 v[174:177], v153 offset:1024
	ds_read_b128 v[178:181], v153 offset:2048
	ds_read_b128 v[182:185], v153 offset:3072
	ds_read_b128 v[186:189], v151 offset:32768
	ds_read_b128 v[190:193], v151 offset:33792
	ds_read_b128 v[194:197], v151 offset:34816
	ds_read_b128 v[198:201], v151 offset:35840
	ds_read_b128 v[202:205], v151 offset:36864
	ds_read_b128 v[206:209], v151 offset:37888
	ds_read_b128 v[210:213], v151 offset:38912
	ds_read_b128 v[214:217], v151 offset:39936
	s_waitcnt vmcnt(8)
	s_waitcnt lgkmcnt(0)
	s_barrier
	s_setprio 1
	s_waitcnt lgkmcnt(0)
	v_mfma_f32_16x16x32_bf16 v[116:119], v[154:157], v[186:189], v[116:119]
	v_mfma_f32_16x16x32_bf16 v[112:115], v[162:165], v[186:189], v[112:115]
	v_mfma_f32_16x16x32_bf16 v[108:111], v[154:157], v[194:197], v[108:111]
	v_mfma_f32_16x16x32_bf16 v[100:103], v[162:165], v[194:197], v[100:103]
	v_mfma_f32_16x16x32_bf16 v[92:95], v[154:157], v[202:205], v[92:95]
	v_mfma_f32_16x16x32_bf16 v[84:87], v[162:165], v[202:205], v[84:87]
	v_mfma_f32_16x16x32_bf16 v[76:79], v[154:157], v[210:213], v[76:79]
	v_mfma_f32_16x16x32_bf16 v[68:71], v[162:165], v[210:213], v[68:71]
	v_mfma_f32_16x16x32_bf16 v[116:119], v[158:161], v[190:193], v[116:119]
	v_mfma_f32_16x16x32_bf16 v[112:115], v[166:169], v[190:193], v[112:115]
	v_mfma_f32_16x16x32_bf16 v[108:111], v[158:161], v[198:201], v[108:111]
	v_mfma_f32_16x16x32_bf16 v[100:103], v[166:169], v[198:201], v[100:103]
	v_mfma_f32_16x16x32_bf16 v[92:95], v[158:161], v[206:209], v[92:95]
	v_mfma_f32_16x16x32_bf16 v[84:87], v[166:169], v[206:209], v[84:87]
	v_mfma_f32_16x16x32_bf16 v[76:79], v[158:161], v[214:217], v[76:79]
	v_mfma_f32_16x16x32_bf16 v[68:71], v[166:169], v[214:217], v[68:71]
	s_setprio 0
	s_setprio 1
	v_mfma_f32_16x16x32_bf16 v[124:127], v[170:173], v[186:189], v[124:127]
	v_mfma_f32_16x16x32_bf16 v[120:123], v[178:181], v[186:189], v[120:123]
	v_mfma_f32_16x16x32_bf16 v[104:107], v[170:173], v[194:197], v[104:107]
	v_mfma_f32_16x16x32_bf16 v[96:99], v[178:181], v[194:197], v[96:99]
	v_mfma_f32_16x16x32_bf16 v[88:91], v[170:173], v[202:205], v[88:91]
	v_mfma_f32_16x16x32_bf16 v[80:83], v[178:181], v[202:205], v[80:83]
	v_mfma_f32_16x16x32_bf16 v[72:75], v[170:173], v[210:213], v[72:75]
	v_mfma_f32_16x16x32_bf16 v[64:67], v[178:181], v[210:213], v[64:67]
	v_mfma_f32_16x16x32_bf16 v[124:127], v[174:177], v[190:193], v[124:127]
	v_mfma_f32_16x16x32_bf16 v[120:123], v[182:185], v[190:193], v[120:123]
	v_mfma_f32_16x16x32_bf16 v[104:107], v[174:177], v[198:201], v[104:107]
	v_mfma_f32_16x16x32_bf16 v[96:99], v[182:185], v[198:201], v[96:99]
	v_mfma_f32_16x16x32_bf16 v[88:91], v[174:177], v[206:209], v[88:91]
	v_mfma_f32_16x16x32_bf16 v[80:83], v[182:185], v[206:209], v[80:83]
	v_mfma_f32_16x16x32_bf16 v[72:75], v[174:177], v[214:217], v[72:75]
	v_mfma_f32_16x16x32_bf16 v[64:67], v[182:185], v[214:217], v[64:67]
	s_setprio 0
	s_barrier
	s_add_i32 s34, s64, s36
	v_lshl_add_u64 v[144:145], v[144:145], 0, s[12:13]
	s_mov_b32 m0, s34
	s_nop 0
	global_load_lds_dwordx4 v[144:145], off
	s_add_i32 m0, s34, 0x2000
	s_add_u32 s30, s30, 0x40080
	v_lshl_add_u64 v[144:145], v[218:219], 0, s[12:13]
	s_addc_u32 s31, s31, 0
	s_add_i32 s34, s65, s36
	global_load_lds_dwordx4 v[144:145], off
	v_lshl_add_u64 v[144:145], s[30:31], 0, v[132:133]
	s_mov_b32 m0, s34
	s_nop 0
	global_load_lds_dwordx4 v[144:145], off
	v_lshl_add_u64 v[144:145], s[30:31], 0, v[128:129]
	s_add_i32 m0, s34, 0x2000
	s_nop 0
	global_load_lds_dwordx4 v[144:145], off
	v_lshl_add_u64 v[144:145], v[220:221], 0, s[12:13]
	s_mov_b32 m0, s42
	s_nop 0
	global_load_lds_dwordx4 v[144:145], off
	v_lshl_add_u64 v[144:145], v[222:223], 0, s[12:13]
	s_mov_b32 m0, s43
	s_nop 0
	global_load_lds_dwordx4 v[144:145], off
	ds_read_b128 v[186:189], v151 offset:49152
	ds_read_b128 v[190:193], v151 offset:50176
	ds_read_b128 v[194:197], v151 offset:51200
	ds_read_b128 v[198:201], v151 offset:52224
	ds_read_b128 v[202:205], v151 offset:53248
	ds_read_b128 v[206:209], v151 offset:54272
	ds_read_b128 v[210:213], v151 offset:55296
	ds_read_b128 v[214:217], v151 offset:56320
	s_waitcnt vmcnt(8)
	s_waitcnt lgkmcnt(0)
	s_barrier
	s_setprio 1
	s_waitcnt lgkmcnt(0)
	v_mfma_f32_16x16x32_bf16 v[60:63], v[154:157], v[186:189], v[60:63]
	v_mfma_f32_16x16x32_bf16 v[52:55], v[162:165], v[186:189], v[52:55]
	v_mfma_f32_16x16x32_bf16 v[44:47], v[154:157], v[194:197], v[44:47]
	v_mfma_f32_16x16x32_bf16 v[36:39], v[162:165], v[194:197], v[36:39]
	v_mfma_f32_16x16x32_bf16 v[28:31], v[154:157], v[202:205], v[28:31]
	v_mfma_f32_16x16x32_bf16 v[20:23], v[162:165], v[202:205], v[20:23]
	v_mfma_f32_16x16x32_bf16 v[12:15], v[154:157], v[210:213], v[12:15]
	v_mfma_f32_16x16x32_bf16 v[4:7], v[162:165], v[210:213], v[4:7]
	v_mfma_f32_16x16x32_bf16 v[60:63], v[158:161], v[190:193], v[60:63]
	v_mfma_f32_16x16x32_bf16 v[52:55], v[166:169], v[190:193], v[52:55]
	v_mfma_f32_16x16x32_bf16 v[44:47], v[158:161], v[198:201], v[44:47]
	v_mfma_f32_16x16x32_bf16 v[36:39], v[166:169], v[198:201], v[36:39]
	v_mfma_f32_16x16x32_bf16 v[28:31], v[158:161], v[206:209], v[28:31]
	v_mfma_f32_16x16x32_bf16 v[20:23], v[166:169], v[206:209], v[20:23]
	v_mfma_f32_16x16x32_bf16 v[12:15], v[158:161], v[214:217], v[12:15]
	v_mfma_f32_16x16x32_bf16 v[4:7], v[166:169], v[214:217], v[4:7]
	s_setprio 0
	s_setprio 1
	v_mfma_f32_16x16x32_bf16 v[56:59], v[170:173], v[186:189], v[56:59]
	v_mfma_f32_16x16x32_bf16 v[48:51], v[178:181], v[186:189], v[48:51]
	v_mfma_f32_16x16x32_bf16 v[40:43], v[170:173], v[194:197], v[40:43]
	v_mfma_f32_16x16x32_bf16 v[32:35], v[178:181], v[194:197], v[32:35]
	v_mfma_f32_16x16x32_bf16 v[24:27], v[170:173], v[202:205], v[24:27]
	v_mfma_f32_16x16x32_bf16 v[16:19], v[178:181], v[202:205], v[16:19]
	v_mfma_f32_16x16x32_bf16 v[8:11], v[170:173], v[210:213], v[8:11]
	v_mfma_f32_16x16x32_bf16 v[0:3], v[178:181], v[210:213], v[0:3]
	v_mfma_f32_16x16x32_bf16 v[56:59], v[174:177], v[190:193], v[56:59]
	v_mfma_f32_16x16x32_bf16 v[48:51], v[182:185], v[190:193], v[48:51]
	v_mfma_f32_16x16x32_bf16 v[40:43], v[174:177], v[198:201], v[40:43]
	v_mfma_f32_16x16x32_bf16 v[32:35], v[182:185], v[198:201], v[32:35]
	v_mfma_f32_16x16x32_bf16 v[24:27], v[174:177], v[206:209], v[24:27]
	v_mfma_f32_16x16x32_bf16 v[16:19], v[182:185], v[206:209], v[16:19]
	v_mfma_f32_16x16x32_bf16 v[8:11], v[174:177], v[214:217], v[8:11]
	v_mfma_f32_16x16x32_bf16 v[0:3], v[182:185], v[214:217], v[0:3]
	s_setprio 0
	s_barrier
	s_add_i32 s63, s63, 2
	s_add_u32 s28, s28, 0x100
	s_addc_u32 s29, s29, 0
	s_add_u32 s61, s61, 0x100
	s_addc_u32 s62, s62, 0
	s_cmp_gt_u32 s63, 13
	s_cbranch_scc0 .LBB0_555
	s_and_b64 vcc, exec, s[14:15]
	s_cbranch_vccz .LBB0_558
	s_barrier

.LBB0_637:
	s_add_u32 s22, s20, 0x100
	s_addc_u32 s23, s21, 0
	s_cmp_eq_u32 s61, 40
	s_cselect_b32 s27, s9, s23
	s_cselect_b32 s26, s8, s22
	s_cselect_b32 s25, s19, s60
	s_cselect_b32 s24, s18, s51
	v_lshl_add_u64 v[206:207], s[20:21], 0, v[200:201]
	s_add_i32 m0, s29, 0xc000
	s_nop 0
	global_load_lds_dwordx4 v[206:207], off
	v_lshl_add_u64 v[206:207], s[20:21], 0, v[202:203]
	s_add_i32 m0, s29, 0xe000
	s_nop 0
	global_load_lds_dwordx4 v[206:207], off
	ds_read_b128 v[120:123], v247
	ds_read_b128 v[124:127], v247 offset:1024
	ds_read_b128 v[128:131], v247 offset:2048
	ds_read_b128 v[132:135], v247 offset:3072
	ds_read_b128 v[140:143], v248
	ds_read_b128 v[148:151], v248 offset:1024
	ds_read_b128 v[152:155], v248 offset:2048
	ds_read_b128 v[156:159], v248 offset:3072
	ds_read_b128 v[160:163], v249
	ds_read_b128 v[164:167], v249 offset:1024
	ds_read_b128 v[168:171], v249 offset:2048
	ds_read_b128 v[172:175], v249 offset:3072
	ds_read_b128 v[176:179], v249 offset:4096
	ds_read_b128 v[180:183], v249 offset:5120
	ds_read_b128 v[184:187], v249 offset:6144
	ds_read_b128 v[188:191], v249 offset:7168
	s_waitcnt vmcnt(8)
	s_waitcnt lgkmcnt(0)
	s_barrier
	s_setprio 1
	s_waitcnt lgkmcnt(0)
	v_mfma_f32_16x16x32_bf16 v[144:147], v[120:123], v[160:163], v[144:147]
	v_mfma_f32_16x16x32_bf16 v[136:139], v[128:131], v[160:163], v[136:139]
	v_mfma_f32_16x16x32_bf16 v[108:111], v[120:123], v[168:171], v[108:111]
	v_mfma_f32_16x16x32_bf16 v[104:107], v[128:131], v[168:171], v[104:107]
	v_mfma_f32_16x16x32_bf16 v[92:95], v[120:123], v[176:179], v[92:95]
	v_mfma_f32_16x16x32_bf16 v[88:91], v[128:131], v[176:179], v[88:91]
	v_mfma_f32_16x16x32_bf16 v[76:79], v[120:123], v[184:187], v[76:79]
	v_mfma_f32_16x16x32_bf16 v[72:75], v[128:131], v[184:187], v[72:75]
	v_mfma_f32_16x16x32_bf16 v[144:147], v[124:127], v[164:167], v[144:147]
	v_mfma_f32_16x16x32_bf16 v[136:139], v[132:135], v[164:167], v[136:139]
	v_mfma_f32_16x16x32_bf16 v[108:111], v[124:127], v[172:175], v[108:111]
	v_mfma_f32_16x16x32_bf16 v[104:107], v[132:135], v[172:175], v[104:107]
	v_mfma_f32_16x16x32_bf16 v[92:95], v[124:127], v[180:183], v[92:95]
	v_mfma_f32_16x16x32_bf16 v[88:91], v[132:135], v[180:183], v[88:91]
	v_mfma_f32_16x16x32_bf16 v[76:79], v[124:127], v[188:191], v[76:79]
	v_mfma_f32_16x16x32_bf16 v[72:75], v[132:135], v[188:191], v[72:75]
	s_setprio 0
	s_setprio 1
	v_mfma_f32_16x16x32_bf16 v[116:119], v[140:143], v[160:163], v[116:119]
	v_mfma_f32_16x16x32_bf16 v[112:115], v[152:155], v[160:163], v[112:115]
	v_mfma_f32_16x16x32_bf16 v[100:103], v[140:143], v[168:171], v[100:103]
	v_mfma_f32_16x16x32_bf16 v[96:99], v[152:155], v[168:171], v[96:99]
	v_mfma_f32_16x16x32_bf16 v[84:87], v[140:143], v[176:179], v[84:87]
	v_mfma_f32_16x16x32_bf16 v[80:83], v[152:155], v[176:179], v[80:83]
	v_mfma_f32_16x16x32_bf16 v[68:71], v[140:143], v[184:187], v[68:71]
	v_mfma_f32_16x16x32_bf16 v[64:67], v[152:155], v[184:187], v[64:67]
	v_mfma_f32_16x16x32_bf16 v[116:119], v[148:151], v[164:167], v[116:119]
	v_mfma_f32_16x16x32_bf16 v[112:115], v[156:159], v[164:167], v[112:115]
	v_mfma_f32_16x16x32_bf16 v[100:103], v[148:151], v[172:175], v[100:103]
	v_mfma_f32_16x16x32_bf16 v[96:99], v[156:159], v[172:175], v[96:99]
	v_mfma_f32_16x16x32_bf16 v[84:87], v[148:151], v[180:183], v[84:87]
	v_mfma_f32_16x16x32_bf16 v[80:83], v[156:159], v[180:183], v[80:83]
	v_mfma_f32_16x16x32_bf16 v[68:71], v[148:151], v[188:191], v[68:71]
	v_mfma_f32_16x16x32_bf16 v[64:67], v[156:159], v[188:191], v[64:67]
	s_setprio 0
	s_barrier
	s_add_i32 s20, s43, s28
	v_lshl_add_u64 v[206:207], s[24:25], 0, v[194:195]
	s_mov_b32 m0, s20
	s_nop 0
	global_load_lds_dwordx4 v[206:207], off
	s_add_i32 m0, s20, 0x2000
	s_add_u32 s20, s24, 0xb0000
	v_lshl_add_u64 v[208:209], s[24:25], 0, v[198:199]
	s_addc_u32 s21, s25, 0
	s_add_i32 s62, s46, s28
	global_load_lds_dwordx4 v[208:209], off
	v_lshl_add_u64 v[210:211], s[20:21], 0, v[194:195]
	s_mov_b32 m0, s62
	v_lshl_add_u64 v[212:213], s[26:27], 0, v[196:197]
	global_load_lds_dwordx4 v[210:211], off
	v_lshl_add_u64 v[210:211], s[20:21], 0, v[198:199]
	s_add_i32 m0, s62, 0x2000
	s_nop 0
	global_load_lds_dwordx4 v[210:211], off
	v_lshl_add_u64 v[210:211], s[26:27], 0, v[192:193]
	s_mov_b32 m0, s29
	s_nop 0
	global_load_lds_dwordx4 v[210:211], off
	s_mov_b32 m0, s30
	s_nop 0
	global_load_lds_dwordx4 v[212:213], off
	ds_read_b128 v[160:163], v249 offset:16384
	ds_read_b128 v[164:167], v249 offset:17408
	ds_read_b128 v[168:171], v249 offset:18432
	ds_read_b128 v[172:175], v249 offset:19456
	ds_read_b128 v[176:179], v249 offset:20480
	ds_read_b128 v[180:183], v249 offset:21504
	ds_read_b128 v[184:187], v249 offset:22528
	ds_read_b128 v[188:191], v249 offset:23552
	s_waitcnt vmcnt(8)
	s_waitcnt lgkmcnt(0)
	s_barrier
	s_setprio 1
	s_waitcnt lgkmcnt(0)
	v_mfma_f32_16x16x32_bf16 v[60:63], v[120:123], v[160:163], v[60:63]
	v_mfma_f32_16x16x32_bf16 v[56:59], v[128:131], v[160:163], v[56:59]
	v_mfma_f32_16x16x32_bf16 v[44:47], v[120:123], v[168:171], v[44:47]
	v_mfma_f32_16x16x32_bf16 v[40:43], v[128:131], v[168:171], v[40:43]
	v_mfma_f32_16x16x32_bf16 v[28:31], v[120:123], v[176:179], v[28:31]
	v_mfma_f32_16x16x32_bf16 v[24:27], v[128:131], v[176:179], v[24:27]
	v_mfma_f32_16x16x32_bf16 v[12:15], v[120:123], v[184:187], v[12:15]
	v_mfma_f32_16x16x32_bf16 v[8:11], v[128:131], v[184:187], v[8:11]
	v_mfma_f32_16x16x32_bf16 v[60:63], v[124:127], v[164:167], v[60:63]
	v_mfma_f32_16x16x32_bf16 v[56:59], v[132:135], v[164:167], v[56:59]
	v_mfma_f32_16x16x32_bf16 v[44:47], v[124:127], v[172:175], v[44:47]
	v_mfma_f32_16x16x32_bf16 v[40:43], v[132:135], v[172:175], v[40:43]
	v_mfma_f32_16x16x32_bf16 v[28:31], v[124:127], v[180:183], v[28:31]
	v_mfma_f32_16x16x32_bf16 v[24:27], v[132:135], v[180:183], v[24:27]
	v_mfma_f32_16x16x32_bf16 v[12:15], v[124:127], v[188:191], v[12:15]
	v_mfma_f32_16x16x32_bf16 v[8:11], v[132:135], v[188:191], v[8:11]
	s_setprio 0
	s_setprio 1
	v_mfma_f32_16x16x32_bf16 v[52:55], v[140:143], v[160:163], v[52:55]
	v_mfma_f32_16x16x32_bf16 v[48:51], v[152:155], v[160:163], v[48:51]
	v_mfma_f32_16x16x32_bf16 v[36:39], v[140:143], v[168:171], v[36:39]
	v_mfma_f32_16x16x32_bf16 v[32:35], v[152:155], v[168:171], v[32:35]
	v_mfma_f32_16x16x32_bf16 v[20:23], v[140:143], v[176:179], v[20:23]
	v_mfma_f32_16x16x32_bf16 v[16:19], v[152:155], v[176:179], v[16:19]
	v_mfma_f32_16x16x32_bf16 v[4:7], v[140:143], v[184:187], v[4:7]
	v_mfma_f32_16x16x32_bf16 v[0:3], v[152:155], v[184:187], v[0:3]
	v_mfma_f32_16x16x32_bf16 v[52:55], v[148:151], v[164:167], v[52:55]
	v_mfma_f32_16x16x32_bf16 v[48:51], v[156:159], v[164:167], v[48:51]
	v_mfma_f32_16x16x32_bf16 v[36:39], v[148:151], v[172:175], v[36:39]
	v_mfma_f32_16x16x32_bf16 v[32:35], v[156:159], v[172:175], v[32:35]
	v_mfma_f32_16x16x32_bf16 v[20:23], v[148:151], v[180:183], v[20:23]
	v_mfma_f32_16x16x32_bf16 v[16:19], v[156:159], v[180:183], v[16:19]
	v_mfma_f32_16x16x32_bf16 v[4:7], v[148:151], v[188:191], v[4:7]
	v_mfma_f32_16x16x32_bf16 v[0:3], v[156:159], v[188:191], v[0:3]
	s_setprio 0
	s_barrier
	s_add_i32 s62, 0, 0x18000
	s_add_i32 s63, 0, 0x1c000
	s_add_u32 s20, s26, 0xb0000
	s_addc_u32 s21, s27, 0
	s_mov_b32 m0, s31
	v_lshl_add_u64 v[214:215], s[20:21], 0, v[192:193]
	global_load_lds_dwordx4 v[214:215], off
	v_lshl_add_u64 v[214:215], s[20:21], 0, v[196:197]
	s_mov_b32 m0, s34
	s_nop 0
	global_load_lds_dwordx4 v[214:215], off
	v_add_u32_e32 v132, s62, v246
	v_add_u32_e32 v156, s63, v246
	ds_read_b128 v[120:123], v132
	ds_read_b128 v[124:127], v132 offset:1024
	ds_read_b128 v[128:131], v132 offset:2048
	ds_read_b128 v[132:135], v132 offset:3072
	ds_read_b128 v[140:143], v156
	ds_read_b128 v[148:151], v156 offset:1024
	ds_read_b128 v[152:155], v156 offset:2048
	ds_read_b128 v[156:159], v156 offset:3072
	ds_read_b128 v[160:163], v249 offset:32768
	ds_read_b128 v[164:167], v249 offset:33792
	ds_read_b128 v[168:171], v249 offset:34816
	ds_read_b128 v[172:175], v249 offset:35840
	ds_read_b128 v[176:179], v249 offset:36864
	ds_read_b128 v[180:183], v249 offset:37888
	ds_read_b128 v[184:187], v249 offset:38912
	ds_read_b128 v[188:191], v249 offset:39936
	s_waitcnt vmcnt(8)
	s_waitcnt lgkmcnt(0)
	s_barrier
	s_setprio 1
	s_waitcnt lgkmcnt(0)
	v_mfma_f32_16x16x32_bf16 v[144:147], v[120:123], v[160:163], v[144:147]
	v_mfma_f32_16x16x32_bf16 v[136:139], v[128:131], v[160:163], v[136:139]
	v_mfma_f32_16x16x32_bf16 v[108:111], v[120:123], v[168:171], v[108:111]
	v_mfma_f32_16x16x32_bf16 v[104:107], v[128:131], v[168:171], v[104:107]
	v_mfma_f32_16x16x32_bf16 v[92:95], v[120:123], v[176:179], v[92:95]
	v_mfma_f32_16x16x32_bf16 v[88:91], v[128:131], v[176:179], v[88:91]
	v_mfma_f32_16x16x32_bf16 v[76:79], v[120:123], v[184:187], v[76:79]
	v_mfma_f32_16x16x32_bf16 v[72:75], v[128:131], v[184:187], v[72:75]
	v_mfma_f32_16x16x32_bf16 v[144:147], v[124:127], v[164:167], v[144:147]
	v_mfma_f32_16x16x32_bf16 v[136:139], v[132:135], v[164:167], v[136:139]
	v_mfma_f32_16x16x32_bf16 v[108:111], v[124:127], v[172:175], v[108:111]
	v_mfma_f32_16x16x32_bf16 v[104:107], v[132:135], v[172:175], v[104:107]
	v_mfma_f32_16x16x32_bf16 v[92:95], v[124:127], v[180:183], v[92:95]
	v_mfma_f32_16x16x32_bf16 v[88:91], v[132:135], v[180:183], v[88:91]
	v_mfma_f32_16x16x32_bf16 v[76:79], v[124:127], v[188:191], v[76:79]
	v_mfma_f32_16x16x32_bf16 v[72:75], v[132:135], v[188:191], v[72:75]
	s_setprio 0
	s_setprio 1
	v_mfma_f32_16x16x32_bf16 v[116:119], v[140:143], v[160:163], v[116:119]
	v_mfma_f32_16x16x32_bf16 v[112:115], v[152:155], v[160:163], v[112:115]
	v_mfma_f32_16x16x32_bf16 v[100:103], v[140:143], v[168:171], v[100:103]
	v_mfma_f32_16x16x32_bf16 v[96:99], v[152:155], v[168:171], v[96:99]
	v_mfma_f32_16x16x32_bf16 v[84:87], v[140:143], v[176:179], v[84:87]
	v_mfma_f32_16x16x32_bf16 v[80:83], v[152:155], v[176:179], v[80:83]
	v_mfma_f32_16x16x32_bf16 v[68:71], v[140:143], v[184:187], v[68:71]
	v_mfma_f32_16x16x32_bf16 v[64:67], v[152:155], v[184:187], v[64:67]
	v_mfma_f32_16x16x32_bf16 v[116:119], v[148:151], v[164:167], v[116:119]
	v_mfma_f32_16x16x32_bf16 v[112:115], v[156:159], v[164:167], v[112:115]
	v_mfma_f32_16x16x32_bf16 v[100:103], v[148:151], v[172:175], v[100:103]
	v_mfma_f32_16x16x32_bf16 v[96:99], v[156:159], v[172:175], v[96:99]
	v_mfma_f32_16x16x32_bf16 v[84:87], v[148:151], v[180:183], v[84:87]
	v_mfma_f32_16x16x32_bf16 v[80:83], v[156:159], v[180:183], v[80:83]
	v_mfma_f32_16x16x32_bf16 v[68:71], v[148:151], v[188:191], v[68:71]
	v_mfma_f32_16x16x32_bf16 v[64:67], v[156:159], v[188:191], v[64:67]
	s_setprio 0
	s_barrier
	s_add_i32 s20, s62, s28
	v_lshl_add_u64 v[206:207], v[206:207], 0, s[14:15]
	s_mov_b32 m0, s20
	s_nop 0
	global_load_lds_dwordx4 v[206:207], off
	s_add_i32 m0, s20, 0x2000
	s_add_u32 s20, s24, 0xb0080
	v_lshl_add_u64 v[206:207], v[208:209], 0, s[14:15]
	s_addc_u32 s21, s25, 0
	s_add_i32 s24, s63, s28
	global_load_lds_dwordx4 v[206:207], off
	v_lshl_add_u64 v[206:207], s[20:21], 0, v[194:195]
	s_mov_b32 m0, s24
	s_nop 0
	global_load_lds_dwordx4 v[206:207], off
	v_lshl_add_u64 v[206:207], s[20:21], 0, v[198:199]
	s_add_i32 m0, s24, 0x2000
	s_nop 0
	global_load_lds_dwordx4 v[206:207], off
	v_lshl_add_u64 v[206:207], v[210:211], 0, s[14:15]
	s_mov_b32 m0, s38
	s_nop 0
	global_load_lds_dwordx4 v[206:207], off
	v_lshl_add_u64 v[206:207], v[212:213], 0, s[14:15]
	s_mov_b32 m0, s39
	s_nop 0
	global_load_lds_dwordx4 v[206:207], off
	ds_read_b128 v[160:163], v249 offset:49152
	ds_read_b128 v[164:167], v249 offset:50176
	ds_read_b128 v[168:171], v249 offset:51200
	ds_read_b128 v[172:175], v249 offset:52224
	ds_read_b128 v[176:179], v249 offset:53248
	ds_read_b128 v[180:183], v249 offset:54272
	ds_read_b128 v[184:187], v249 offset:55296
	ds_read_b128 v[188:191], v249 offset:56320
	s_waitcnt vmcnt(8)
	s_waitcnt lgkmcnt(0)
	s_barrier
	s_setprio 1
	s_waitcnt lgkmcnt(0)
	v_mfma_f32_16x16x32_bf16 v[60:63], v[120:123], v[160:163], v[60:63]
	v_mfma_f32_16x16x32_bf16 v[56:59], v[128:131], v[160:163], v[56:59]
	v_mfma_f32_16x16x32_bf16 v[44:47], v[120:123], v[168:171], v[44:47]
	v_mfma_f32_16x16x32_bf16 v[40:43], v[128:131], v[168:171], v[40:43]
	v_mfma_f32_16x16x32_bf16 v[28:31], v[120:123], v[176:179], v[28:31]
	v_mfma_f32_16x16x32_bf16 v[24:27], v[128:131], v[176:179], v[24:27]
	v_mfma_f32_16x16x32_bf16 v[12:15], v[120:123], v[184:187], v[12:15]
	v_mfma_f32_16x16x32_bf16 v[8:11], v[128:131], v[184:187], v[8:11]
	v_mfma_f32_16x16x32_bf16 v[60:63], v[124:127], v[164:167], v[60:63]
	v_mfma_f32_16x16x32_bf16 v[56:59], v[132:135], v[164:167], v[56:59]
	v_mfma_f32_16x16x32_bf16 v[44:47], v[124:127], v[172:175], v[44:47]
	v_mfma_f32_16x16x32_bf16 v[40:43], v[132:135], v[172:175], v[40:43]
	v_mfma_f32_16x16x32_bf16 v[28:31], v[124:127], v[180:183], v[28:31]
	v_mfma_f32_16x16x32_bf16 v[24:27], v[132:135], v[180:183], v[24:27]
	v_mfma_f32_16x16x32_bf16 v[12:15], v[124:127], v[188:191], v[12:15]
	v_mfma_f32_16x16x32_bf16 v[8:11], v[132:135], v[188:191], v[8:11]
	s_setprio 0
	s_setprio 1
	v_mfma_f32_16x16x32_bf16 v[52:55], v[140:143], v[160:163], v[52:55]
	v_mfma_f32_16x16x32_bf16 v[48:51], v[152:155], v[160:163], v[48:51]
	v_mfma_f32_16x16x32_bf16 v[36:39], v[140:143], v[168:171], v[36:39]
	v_mfma_f32_16x16x32_bf16 v[32:35], v[152:155], v[168:171], v[32:35]
	v_mfma_f32_16x16x32_bf16 v[20:23], v[140:143], v[176:179], v[20:23]
	v_mfma_f32_16x16x32_bf16 v[16:19], v[152:155], v[176:179], v[16:19]
	v_mfma_f32_16x16x32_bf16 v[4:7], v[140:143], v[184:187], v[4:7]
	v_mfma_f32_16x16x32_bf16 v[0:3], v[152:155], v[184:187], v[0:3]
	v_mfma_f32_16x16x32_bf16 v[52:55], v[148:151], v[164:167], v[52:55]
	v_mfma_f32_16x16x32_bf16 v[48:51], v[156:159], v[164:167], v[48:51]
	v_mfma_f32_16x16x32_bf16 v[36:39], v[148:151], v[172:175], v[36:39]
	v_mfma_f32_16x16x32_bf16 v[32:35], v[156:159], v[172:175], v[32:35]
	v_mfma_f32_16x16x32_bf16 v[20:23], v[148:151], v[180:183], v[20:23]
	v_mfma_f32_16x16x32_bf16 v[16:19], v[156:159], v[180:183], v[16:19]
	v_mfma_f32_16x16x32_bf16 v[4:7], v[148:151], v[188:191], v[4:7]
	v_mfma_f32_16x16x32_bf16 v[0:3], v[156:159], v[188:191], v[0:3]
	s_setprio 0
	s_barrier
	s_add_i32 s61, s61, 2
	s_add_u32 s51, s51, 0x100
	s_addc_u32 s60, s60, 0
	s_cmp_gt_u32 s61, 41
	s_mov_b64 s[20:21], s[22:23]
	s_cbranch_scc0 .LBB0_637
	s_and_b64 vcc, exec, s[16:17]
	s_cbranch_vccz .LBB0_640
	s_barrier

.LBB0_723:
	s_add_u32 s62, s48, 0xfffc0080
	s_addc_u32 s63, s49, -1
	s_cmp_eq_u32 s93, 12
	s_cselect_b32 s65, s9, s63
	s_cselect_b32 s64, s41, s62
	s_cselect_b32 s63, s39, s61
	s_cselect_b32 s62, s51, s60
	v_lshl_add_u64 v[192:193], s[48:49], 0, v[214:215]
	s_add_i32 m0, s69, 0xc000
	s_nop 0
	global_load_lds_dwordx4 v[192:193], off
	v_lshl_add_u64 v[192:193], s[48:49], 0, v[216:217]
	s_add_i32 m0, s69, 0xe000
	s_nop 0
	global_load_lds_dwordx4 v[192:193], off
	ds_read_b128 v[128:131], v235
	ds_read_b128 v[132:135], v235 offset:1024
	ds_read_b128 v[136:139], v235 offset:2048
	ds_read_b128 v[140:143], v235 offset:3072
	ds_read_b128 v[144:147], v236
	ds_read_b128 v[148:151], v236 offset:1024
	ds_read_b128 v[152:155], v236 offset:2048
	ds_read_b128 v[156:159], v236 offset:3072
	ds_read_b128 v[160:163], v237
	ds_read_b128 v[164:167], v237 offset:1024
	ds_read_b128 v[168:171], v237 offset:2048
	ds_read_b128 v[172:175], v237 offset:3072
	ds_read_b128 v[176:179], v237 offset:4096
	ds_read_b128 v[180:183], v237 offset:5120
	ds_read_b128 v[184:187], v237 offset:6144
	ds_read_b128 v[188:191], v237 offset:7168
	s_waitcnt vmcnt(8)
	s_waitcnt lgkmcnt(0)
	s_barrier
	s_setprio 1
	s_waitcnt lgkmcnt(0)
	v_mfma_f32_16x16x32_bf16 v[124:127], v[128:131], v[160:163], v[124:127]
	v_mfma_f32_16x16x32_bf16 v[120:123], v[136:139], v[160:163], v[120:123]
	v_mfma_f32_16x16x32_bf16 v[116:119], v[128:131], v[168:171], v[116:119]
	v_mfma_f32_16x16x32_bf16 v[112:115], v[136:139], v[168:171], v[112:115]
	v_mfma_f32_16x16x32_bf16 v[108:111], v[128:131], v[176:179], v[108:111]
	v_mfma_f32_16x16x32_bf16 v[100:103], v[136:139], v[176:179], v[100:103]
	v_mfma_f32_16x16x32_bf16 v[92:95], v[128:131], v[184:187], v[92:95]
	v_mfma_f32_16x16x32_bf16 v[80:83], v[136:139], v[184:187], v[80:83]
	v_mfma_f32_16x16x32_bf16 v[124:127], v[132:135], v[164:167], v[124:127]
	v_mfma_f32_16x16x32_bf16 v[120:123], v[140:143], v[164:167], v[120:123]
	v_mfma_f32_16x16x32_bf16 v[116:119], v[132:135], v[172:175], v[116:119]
	v_mfma_f32_16x16x32_bf16 v[112:115], v[140:143], v[172:175], v[112:115]
	v_mfma_f32_16x16x32_bf16 v[108:111], v[132:135], v[180:183], v[108:111]
	v_mfma_f32_16x16x32_bf16 v[100:103], v[140:143], v[180:183], v[100:103]
	v_mfma_f32_16x16x32_bf16 v[92:95], v[132:135], v[188:191], v[92:95]
	v_mfma_f32_16x16x32_bf16 v[80:83], v[140:143], v[188:191], v[80:83]
	s_setprio 0
	s_setprio 1
	v_mfma_f32_16x16x32_bf16 v[104:107], v[144:147], v[160:163], v[104:107]
	v_mfma_f32_16x16x32_bf16 v[96:99], v[152:155], v[160:163], v[96:99]
	v_mfma_f32_16x16x32_bf16 v[88:91], v[144:147], v[168:171], v[88:91]
	v_mfma_f32_16x16x32_bf16 v[84:87], v[152:155], v[168:171], v[84:87]
	v_mfma_f32_16x16x32_bf16 v[76:79], v[144:147], v[176:179], v[76:79]
	v_mfma_f32_16x16x32_bf16 v[72:75], v[152:155], v[176:179], v[72:75]
	v_mfma_f32_16x16x32_bf16 v[68:71], v[144:147], v[184:187], v[68:71]
	v_mfma_f32_16x16x32_bf16 v[64:67], v[152:155], v[184:187], v[64:67]
	v_mfma_f32_16x16x32_bf16 v[104:107], v[148:151], v[164:167], v[104:107]
	v_mfma_f32_16x16x32_bf16 v[96:99], v[156:159], v[164:167], v[96:99]
	v_mfma_f32_16x16x32_bf16 v[88:91], v[148:151], v[172:175], v[88:91]
	v_mfma_f32_16x16x32_bf16 v[84:87], v[156:159], v[172:175], v[84:87]
	v_mfma_f32_16x16x32_bf16 v[76:79], v[148:151], v[180:183], v[76:79]
	v_mfma_f32_16x16x32_bf16 v[72:75], v[156:159], v[180:183], v[72:75]
	v_mfma_f32_16x16x32_bf16 v[68:71], v[148:151], v[188:191], v[68:71]
	v_mfma_f32_16x16x32_bf16 v[64:67], v[156:159], v[188:191], v[64:67]
	s_setprio 0
	s_barrier
	s_add_i32 s94, s88, s68
	v_lshl_add_u64 v[192:193], s[62:63], 0, v[208:209]
	s_mov_b32 m0, s94
	s_nop 0
	global_load_lds_dwordx4 v[192:193], off
	s_add_i32 m0, s94, 0x2000
	s_add_u32 s94, s62, 0x40000
	v_lshl_add_u64 v[194:195], s[62:63], 0, v[212:213]
	s_addc_u32 s95, s63, 0
	s_add_i32 s96, s89, s68
	global_load_lds_dwordx4 v[194:195], off
	v_lshl_add_u64 v[196:197], s[94:95], 0, v[208:209]
	s_mov_b32 m0, s96
	v_lshl_add_u64 v[198:199], s[64:65], 0, v[210:211]
	global_load_lds_dwordx4 v[196:197], off
	v_lshl_add_u64 v[196:197], s[94:95], 0, v[212:213]
	s_add_i32 m0, s96, 0x2000
	s_nop 0
	global_load_lds_dwordx4 v[196:197], off
	v_lshl_add_u64 v[196:197], s[64:65], 0, v[206:207]
	s_mov_b32 m0, s69
	s_nop 0
	global_load_lds_dwordx4 v[196:197], off
	s_mov_b32 m0, s70
	s_nop 0
	global_load_lds_dwordx4 v[198:199], off
	ds_read_b128 v[160:163], v237 offset:16384
	ds_read_b128 v[164:167], v237 offset:17408
	ds_read_b128 v[168:171], v237 offset:18432
	ds_read_b128 v[172:175], v237 offset:19456
	ds_read_b128 v[176:179], v237 offset:20480
	ds_read_b128 v[180:183], v237 offset:21504
	ds_read_b128 v[184:187], v237 offset:22528
	ds_read_b128 v[188:191], v237 offset:23552
	s_waitcnt vmcnt(8)
	s_waitcnt lgkmcnt(0)
	s_barrier
	s_setprio 1
	s_waitcnt lgkmcnt(0)
	v_mfma_f32_16x16x32_bf16 v[60:63], v[128:131], v[160:163], v[60:63]
	v_mfma_f32_16x16x32_bf16 v[56:59], v[136:139], v[160:163], v[56:59]
	v_mfma_f32_16x16x32_bf16 v[48:51], v[128:131], v[168:171], v[48:51]
	v_mfma_f32_16x16x32_bf16 v[40:43], v[136:139], v[168:171], v[40:43]
	v_mfma_f32_16x16x32_bf16 v[32:35], v[128:131], v[176:179], v[32:35]
	v_mfma_f32_16x16x32_bf16 v[24:27], v[136:139], v[176:179], v[24:27]
	v_mfma_f32_16x16x32_bf16 v[16:19], v[128:131], v[184:187], v[16:19]
	v_mfma_f32_16x16x32_bf16 v[8:11], v[136:139], v[184:187], v[8:11]
	v_mfma_f32_16x16x32_bf16 v[60:63], v[132:135], v[164:167], v[60:63]
	v_mfma_f32_16x16x32_bf16 v[56:59], v[140:143], v[164:167], v[56:59]
	v_mfma_f32_16x16x32_bf16 v[48:51], v[132:135], v[172:175], v[48:51]
	v_mfma_f32_16x16x32_bf16 v[40:43], v[140:143], v[172:175], v[40:43]
	v_mfma_f32_16x16x32_bf16 v[32:35], v[132:135], v[180:183], v[32:35]
	v_mfma_f32_16x16x32_bf16 v[24:27], v[140:143], v[180:183], v[24:27]
	v_mfma_f32_16x16x32_bf16 v[16:19], v[132:135], v[188:191], v[16:19]
	v_mfma_f32_16x16x32_bf16 v[8:11], v[140:143], v[188:191], v[8:11]
	s_setprio 0
	s_setprio 1
	v_mfma_f32_16x16x32_bf16 v[52:55], v[144:147], v[160:163], v[52:55]
	v_mfma_f32_16x16x32_bf16 v[44:47], v[152:155], v[160:163], v[44:47]
	v_mfma_f32_16x16x32_bf16 v[36:39], v[144:147], v[168:171], v[36:39]
	v_mfma_f32_16x16x32_bf16 v[28:31], v[152:155], v[168:171], v[28:31]
	v_mfma_f32_16x16x32_bf16 v[20:23], v[144:147], v[176:179], v[20:23]
	v_mfma_f32_16x16x32_bf16 v[12:15], v[152:155], v[176:179], v[12:15]
	v_mfma_f32_16x16x32_bf16 v[4:7], v[144:147], v[184:187], v[4:7]
	v_mfma_f32_16x16x32_bf16 v[0:3], v[152:155], v[184:187], v[0:3]
	v_mfma_f32_16x16x32_bf16 v[52:55], v[148:151], v[164:167], v[52:55]
	v_mfma_f32_16x16x32_bf16 v[44:47], v[156:159], v[164:167], v[44:47]
	v_mfma_f32_16x16x32_bf16 v[36:39], v[148:151], v[172:175], v[36:39]
	v_mfma_f32_16x16x32_bf16 v[28:31], v[156:159], v[172:175], v[28:31]
	v_mfma_f32_16x16x32_bf16 v[20:23], v[148:151], v[180:183], v[20:23]
	v_mfma_f32_16x16x32_bf16 v[12:15], v[156:159], v[180:183], v[12:15]
	v_mfma_f32_16x16x32_bf16 v[4:7], v[148:151], v[188:191], v[4:7]
	v_mfma_f32_16x16x32_bf16 v[0:3], v[156:159], v[188:191], v[0:3]
	s_setprio 0
	s_barrier
	s_add_i32 s94, 0, 0x18000
	s_add_i32 s95, 0, 0x1c000
	s_add_u32 s64, s64, 0x40000
	s_addc_u32 s65, s65, 0
	s_mov_b32 m0, s71
	v_lshl_add_u64 v[200:201], s[64:65], 0, v[206:207]
	global_load_lds_dwordx4 v[200:201], off
	v_lshl_add_u64 v[200:201], s[64:65], 0, v[210:211]
	s_mov_b32 m0, s72
	s_nop 0
	global_load_lds_dwordx4 v[200:201], off
	v_add_u32_e32 v140, s94, v234
	v_add_u32_e32 v156, s95, v234
	ds_read_b128 v[128:131], v140
	ds_read_b128 v[132:135], v140 offset:1024
	ds_read_b128 v[136:139], v140 offset:2048
	ds_read_b128 v[140:143], v140 offset:3072
	ds_read_b128 v[144:147], v156
	ds_read_b128 v[148:151], v156 offset:1024
	ds_read_b128 v[152:155], v156 offset:2048
	ds_read_b128 v[156:159], v156 offset:3072
	ds_read_b128 v[160:163], v237 offset:32768
	ds_read_b128 v[164:167], v237 offset:33792
	ds_read_b128 v[168:171], v237 offset:34816
	ds_read_b128 v[172:175], v237 offset:35840
	ds_read_b128 v[176:179], v237 offset:36864
	ds_read_b128 v[180:183], v237 offset:37888
	ds_read_b128 v[184:187], v237 offset:38912
	ds_read_b128 v[188:191], v237 offset:39936
	s_waitcnt vmcnt(8)
	s_waitcnt lgkmcnt(0)
	s_barrier
	s_setprio 1
	s_waitcnt lgkmcnt(0)
	v_mfma_f32_16x16x32_bf16 v[124:127], v[128:131], v[160:163], v[124:127]
	v_mfma_f32_16x16x32_bf16 v[120:123], v[136:139], v[160:163], v[120:123]
	v_mfma_f32_16x16x32_bf16 v[116:119], v[128:131], v[168:171], v[116:119]
	v_mfma_f32_16x16x32_bf16 v[112:115], v[136:139], v[168:171], v[112:115]
	v_mfma_f32_16x16x32_bf16 v[108:111], v[128:131], v[176:179], v[108:111]
	v_mfma_f32_16x16x32_bf16 v[100:103], v[136:139], v[176:179], v[100:103]
	v_mfma_f32_16x16x32_bf16 v[92:95], v[128:131], v[184:187], v[92:95]
	v_mfma_f32_16x16x32_bf16 v[80:83], v[136:139], v[184:187], v[80:83]
	v_mfma_f32_16x16x32_bf16 v[124:127], v[132:135], v[164:167], v[124:127]
	v_mfma_f32_16x16x32_bf16 v[120:123], v[140:143], v[164:167], v[120:123]
	v_mfma_f32_16x16x32_bf16 v[116:119], v[132:135], v[172:175], v[116:119]
	v_mfma_f32_16x16x32_bf16 v[112:115], v[140:143], v[172:175], v[112:115]
	v_mfma_f32_16x16x32_bf16 v[108:111], v[132:135], v[180:183], v[108:111]
	v_mfma_f32_16x16x32_bf16 v[100:103], v[140:143], v[180:183], v[100:103]
	v_mfma_f32_16x16x32_bf16 v[92:95], v[132:135], v[188:191], v[92:95]
	v_mfma_f32_16x16x32_bf16 v[80:83], v[140:143], v[188:191], v[80:83]
	s_setprio 0
	s_setprio 1
	v_mfma_f32_16x16x32_bf16 v[104:107], v[144:147], v[160:163], v[104:107]
	v_mfma_f32_16x16x32_bf16 v[96:99], v[152:155], v[160:163], v[96:99]
	v_mfma_f32_16x16x32_bf16 v[88:91], v[144:147], v[168:171], v[88:91]
	v_mfma_f32_16x16x32_bf16 v[84:87], v[152:155], v[168:171], v[84:87]
	v_mfma_f32_16x16x32_bf16 v[76:79], v[144:147], v[176:179], v[76:79]
	v_mfma_f32_16x16x32_bf16 v[72:75], v[152:155], v[176:179], v[72:75]
	v_mfma_f32_16x16x32_bf16 v[68:71], v[144:147], v[184:187], v[68:71]
	v_mfma_f32_16x16x32_bf16 v[64:67], v[152:155], v[184:187], v[64:67]
	v_mfma_f32_16x16x32_bf16 v[104:107], v[148:151], v[164:167], v[104:107]
	v_mfma_f32_16x16x32_bf16 v[96:99], v[156:159], v[164:167], v[96:99]
	v_mfma_f32_16x16x32_bf16 v[88:91], v[148:151], v[172:175], v[88:91]
	v_mfma_f32_16x16x32_bf16 v[84:87], v[156:159], v[172:175], v[84:87]
	v_mfma_f32_16x16x32_bf16 v[76:79], v[148:151], v[180:183], v[76:79]
	v_mfma_f32_16x16x32_bf16 v[72:75], v[156:159], v[180:183], v[72:75]
	v_mfma_f32_16x16x32_bf16 v[68:71], v[148:151], v[188:191], v[68:71]
	v_mfma_f32_16x16x32_bf16 v[64:67], v[156:159], v[188:191], v[64:67]
	s_setprio 0
	s_barrier
	s_add_i32 s64, s94, s68
	v_lshl_add_u64 v[192:193], v[192:193], 0, s[14:15]
	s_mov_b32 m0, s64
	s_nop 0
	global_load_lds_dwordx4 v[192:193], off
	s_add_i32 m0, s64, 0x2000
	s_add_u32 s62, s62, 0x40080
	v_lshl_add_u64 v[192:193], v[194:195], 0, s[14:15]
	s_addc_u32 s63, s63, 0
	s_add_i32 s64, s95, s68
	global_load_lds_dwordx4 v[192:193], off
	v_lshl_add_u64 v[192:193], s[62:63], 0, v[208:209]
	s_mov_b32 m0, s64
	s_nop 0
	global_load_lds_dwordx4 v[192:193], off
	v_lshl_add_u64 v[192:193], s[62:63], 0, v[212:213]
	s_add_i32 m0, s64, 0x2000
	s_nop 0
	global_load_lds_dwordx4 v[192:193], off
	v_lshl_add_u64 v[192:193], v[196:197], 0, s[14:15]
	s_mov_b32 m0, s76
	s_nop 0
	global_load_lds_dwordx4 v[192:193], off
	v_lshl_add_u64 v[192:193], v[198:199], 0, s[14:15]
	s_mov_b32 m0, s77
	s_nop 0
	global_load_lds_dwordx4 v[192:193], off
	ds_read_b128 v[160:163], v237 offset:49152
	ds_read_b128 v[164:167], v237 offset:50176
	ds_read_b128 v[168:171], v237 offset:51200
	ds_read_b128 v[172:175], v237 offset:52224
	ds_read_b128 v[176:179], v237 offset:53248
	ds_read_b128 v[180:183], v237 offset:54272
	ds_read_b128 v[184:187], v237 offset:55296
	ds_read_b128 v[188:191], v237 offset:56320
	s_waitcnt vmcnt(8)
	s_waitcnt lgkmcnt(0)
	s_barrier
	s_setprio 1
	s_waitcnt lgkmcnt(0)
	v_mfma_f32_16x16x32_bf16 v[60:63], v[128:131], v[160:163], v[60:63]
	v_mfma_f32_16x16x32_bf16 v[56:59], v[136:139], v[160:163], v[56:59]
	v_mfma_f32_16x16x32_bf16 v[48:51], v[128:131], v[168:171], v[48:51]
	v_mfma_f32_16x16x32_bf16 v[40:43], v[136:139], v[168:171], v[40:43]
	v_mfma_f32_16x16x32_bf16 v[32:35], v[128:131], v[176:179], v[32:35]
	v_mfma_f32_16x16x32_bf16 v[24:27], v[136:139], v[176:179], v[24:27]
	v_mfma_f32_16x16x32_bf16 v[16:19], v[128:131], v[184:187], v[16:19]
	v_mfma_f32_16x16x32_bf16 v[8:11], v[136:139], v[184:187], v[8:11]
	v_mfma_f32_16x16x32_bf16 v[60:63], v[132:135], v[164:167], v[60:63]
	v_mfma_f32_16x16x32_bf16 v[56:59], v[140:143], v[164:167], v[56:59]
	v_mfma_f32_16x16x32_bf16 v[48:51], v[132:135], v[172:175], v[48:51]
	v_mfma_f32_16x16x32_bf16 v[40:43], v[140:143], v[172:175], v[40:43]
	v_mfma_f32_16x16x32_bf16 v[32:35], v[132:135], v[180:183], v[32:35]
	v_mfma_f32_16x16x32_bf16 v[24:27], v[140:143], v[180:183], v[24:27]
	v_mfma_f32_16x16x32_bf16 v[16:19], v[132:135], v[188:191], v[16:19]
	v_mfma_f32_16x16x32_bf16 v[8:11], v[140:143], v[188:191], v[8:11]
	s_setprio 0
	s_setprio 1
	v_mfma_f32_16x16x32_bf16 v[52:55], v[144:147], v[160:163], v[52:55]
	v_mfma_f32_16x16x32_bf16 v[44:47], v[152:155], v[160:163], v[44:47]
	v_mfma_f32_16x16x32_bf16 v[36:39], v[144:147], v[168:171], v[36:39]
	v_mfma_f32_16x16x32_bf16 v[28:31], v[152:155], v[168:171], v[28:31]
	v_mfma_f32_16x16x32_bf16 v[20:23], v[144:147], v[176:179], v[20:23]
	v_mfma_f32_16x16x32_bf16 v[12:15], v[152:155], v[176:179], v[12:15]
	v_mfma_f32_16x16x32_bf16 v[4:7], v[144:147], v[184:187], v[4:7]
	v_mfma_f32_16x16x32_bf16 v[0:3], v[152:155], v[184:187], v[0:3]
	v_mfma_f32_16x16x32_bf16 v[52:55], v[148:151], v[164:167], v[52:55]
	v_mfma_f32_16x16x32_bf16 v[44:47], v[156:159], v[164:167], v[44:47]
	v_mfma_f32_16x16x32_bf16 v[36:39], v[148:151], v[172:175], v[36:39]
	v_mfma_f32_16x16x32_bf16 v[28:31], v[156:159], v[172:175], v[28:31]
	v_mfma_f32_16x16x32_bf16 v[20:23], v[148:151], v[180:183], v[20:23]
	v_mfma_f32_16x16x32_bf16 v[12:15], v[156:159], v[180:183], v[12:15]
	v_mfma_f32_16x16x32_bf16 v[4:7], v[148:151], v[188:191], v[4:7]
	v_mfma_f32_16x16x32_bf16 v[0:3], v[156:159], v[188:191], v[0:3]
	s_setprio 0
	s_barrier
	s_add_i32 s93, s93, 2
	s_add_u32 s48, s48, 0x100
	s_addc_u32 s49, s49, 0
	s_add_u32 s60, s60, 0x100
	s_addc_u32 s61, s61, 0
	s_cmp_gt_u32 s93, 13
	s_cbranch_scc0 .LBB0_723
	s_and_b64 vcc, exec, s[16:17]
	s_cbranch_vccz .LBB0_726
	s_barrier

.LBB0_1109:
	s_add_u32 s30, s28, 0xfffc0080
	s_addc_u32 s31, s29, -1
	s_cmp_eq_u32 s64, 12
	s_cselect_b32 s35, s19, s31
	s_cselect_b32 s34, s25, s30
	s_cselect_b32 s31, s17, s63
	s_cselect_b32 s30, s61, s62
	v_lshl_add_u64 v[206:207], s[28:29], 0, v[200:201]
	s_add_i32 m0, s27, 0xc000
	s_nop 0
	global_load_lds_dwordx4 v[206:207], off
	v_lshl_add_u64 v[206:207], s[28:29], 0, v[202:203]
	s_add_i32 m0, s27, 0xe000
	s_nop 0
	global_load_lds_dwordx4 v[206:207], off
	ds_read_b128 v[120:123], v246
	ds_read_b128 v[124:127], v246 offset:1024
	ds_read_b128 v[128:131], v246 offset:2048
	ds_read_b128 v[132:135], v246 offset:3072
	ds_read_b128 v[140:143], v247
	ds_read_b128 v[148:151], v247 offset:1024
	ds_read_b128 v[152:155], v247 offset:2048
	ds_read_b128 v[156:159], v247 offset:3072
	ds_read_b128 v[160:163], v248
	ds_read_b128 v[164:167], v248 offset:1024
	ds_read_b128 v[168:171], v248 offset:2048
	ds_read_b128 v[172:175], v248 offset:3072
	ds_read_b128 v[176:179], v248 offset:4096
	ds_read_b128 v[180:183], v248 offset:5120
	ds_read_b128 v[184:187], v248 offset:6144
	ds_read_b128 v[188:191], v248 offset:7168
	s_waitcnt vmcnt(8)
	s_waitcnt lgkmcnt(0)
	s_barrier
	s_setprio 1
	s_waitcnt lgkmcnt(0)
	v_mfma_f32_16x16x32_bf16 v[144:147], v[120:123], v[160:163], v[144:147]
	v_mfma_f32_16x16x32_bf16 v[136:139], v[128:131], v[160:163], v[136:139]
	v_mfma_f32_16x16x32_bf16 v[108:111], v[120:123], v[168:171], v[108:111]
	v_mfma_f32_16x16x32_bf16 v[104:107], v[128:131], v[168:171], v[104:107]
	v_mfma_f32_16x16x32_bf16 v[92:95], v[120:123], v[176:179], v[92:95]
	v_mfma_f32_16x16x32_bf16 v[88:91], v[128:131], v[176:179], v[88:91]
	v_mfma_f32_16x16x32_bf16 v[76:79], v[120:123], v[184:187], v[76:79]
	v_mfma_f32_16x16x32_bf16 v[72:75], v[128:131], v[184:187], v[72:75]
	v_mfma_f32_16x16x32_bf16 v[144:147], v[124:127], v[164:167], v[144:147]
	v_mfma_f32_16x16x32_bf16 v[136:139], v[132:135], v[164:167], v[136:139]
	v_mfma_f32_16x16x32_bf16 v[108:111], v[124:127], v[172:175], v[108:111]
	v_mfma_f32_16x16x32_bf16 v[104:107], v[132:135], v[172:175], v[104:107]
	v_mfma_f32_16x16x32_bf16 v[92:95], v[124:127], v[180:183], v[92:95]
	v_mfma_f32_16x16x32_bf16 v[88:91], v[132:135], v[180:183], v[88:91]
	v_mfma_f32_16x16x32_bf16 v[76:79], v[124:127], v[188:191], v[76:79]
	v_mfma_f32_16x16x32_bf16 v[72:75], v[132:135], v[188:191], v[72:75]
	s_setprio 0
	s_setprio 1
	v_mfma_f32_16x16x32_bf16 v[116:119], v[140:143], v[160:163], v[116:119]
	v_mfma_f32_16x16x32_bf16 v[112:115], v[152:155], v[160:163], v[112:115]
	v_mfma_f32_16x16x32_bf16 v[100:103], v[140:143], v[168:171], v[100:103]
	v_mfma_f32_16x16x32_bf16 v[96:99], v[152:155], v[168:171], v[96:99]
	v_mfma_f32_16x16x32_bf16 v[84:87], v[140:143], v[176:179], v[84:87]
	v_mfma_f32_16x16x32_bf16 v[80:83], v[152:155], v[176:179], v[80:83]
	v_mfma_f32_16x16x32_bf16 v[68:71], v[140:143], v[184:187], v[68:71]
	v_mfma_f32_16x16x32_bf16 v[64:67], v[152:155], v[184:187], v[64:67]
	v_mfma_f32_16x16x32_bf16 v[116:119], v[148:151], v[164:167], v[116:119]
	v_mfma_f32_16x16x32_bf16 v[112:115], v[156:159], v[164:167], v[112:115]
	v_mfma_f32_16x16x32_bf16 v[100:103], v[148:151], v[172:175], v[100:103]
	v_mfma_f32_16x16x32_bf16 v[96:99], v[156:159], v[172:175], v[96:99]
	v_mfma_f32_16x16x32_bf16 v[84:87], v[148:151], v[180:183], v[84:87]
	v_mfma_f32_16x16x32_bf16 v[80:83], v[156:159], v[180:183], v[80:83]
	v_mfma_f32_16x16x32_bf16 v[68:71], v[148:151], v[188:191], v[68:71]
	v_mfma_f32_16x16x32_bf16 v[64:67], v[156:159], v[188:191], v[64:67]
	s_setprio 0
	s_barrier
	s_add_i32 s65, s51, s37
	v_lshl_add_u64 v[206:207], s[30:31], 0, v[194:195]
	s_mov_b32 m0, s65
	s_nop 0
	global_load_lds_dwordx4 v[206:207], off
	s_add_i32 m0, s65, 0x2000
	s_add_u32 s66, s30, 0x40000
	v_lshl_add_u64 v[208:209], s[30:31], 0, v[198:199]
	s_addc_u32 s67, s31, 0
	s_add_i32 s65, s60, s37
	global_load_lds_dwordx4 v[208:209], off
	v_lshl_add_u64 v[210:211], s[66:67], 0, v[194:195]
	s_mov_b32 m0, s65
	v_lshl_add_u64 v[212:213], s[34:35], 0, v[196:197]
	global_load_lds_dwordx4 v[210:211], off
	v_lshl_add_u64 v[210:211], s[66:67], 0, v[198:199]
	s_add_i32 m0, s65, 0x2000
	s_nop 0
	global_load_lds_dwordx4 v[210:211], off
	v_lshl_add_u64 v[210:211], s[34:35], 0, v[192:193]
	s_mov_b32 m0, s27
	s_nop 0
	global_load_lds_dwordx4 v[210:211], off
	s_mov_b32 m0, s38
	s_nop 0
	global_load_lds_dwordx4 v[212:213], off
	ds_read_b128 v[160:163], v248 offset:16384
	ds_read_b128 v[164:167], v248 offset:17408
	ds_read_b128 v[168:171], v248 offset:18432
	ds_read_b128 v[172:175], v248 offset:19456
	ds_read_b128 v[176:179], v248 offset:20480
	ds_read_b128 v[180:183], v248 offset:21504
	ds_read_b128 v[184:187], v248 offset:22528
	ds_read_b128 v[188:191], v248 offset:23552
	s_waitcnt vmcnt(8)
	s_waitcnt lgkmcnt(0)
	s_barrier
	s_setprio 1
	s_waitcnt lgkmcnt(0)
	v_mfma_f32_16x16x32_bf16 v[60:63], v[120:123], v[160:163], v[60:63]
	v_mfma_f32_16x16x32_bf16 v[56:59], v[128:131], v[160:163], v[56:59]
	v_mfma_f32_16x16x32_bf16 v[44:47], v[120:123], v[168:171], v[44:47]
	v_mfma_f32_16x16x32_bf16 v[40:43], v[128:131], v[168:171], v[40:43]
	v_mfma_f32_16x16x32_bf16 v[28:31], v[120:123], v[176:179], v[28:31]
	v_mfma_f32_16x16x32_bf16 v[24:27], v[128:131], v[176:179], v[24:27]
	v_mfma_f32_16x16x32_bf16 v[12:15], v[120:123], v[184:187], v[12:15]
	v_mfma_f32_16x16x32_bf16 v[8:11], v[128:131], v[184:187], v[8:11]
	v_mfma_f32_16x16x32_bf16 v[60:63], v[124:127], v[164:167], v[60:63]
	v_mfma_f32_16x16x32_bf16 v[56:59], v[132:135], v[164:167], v[56:59]
	v_mfma_f32_16x16x32_bf16 v[44:47], v[124:127], v[172:175], v[44:47]
	v_mfma_f32_16x16x32_bf16 v[40:43], v[132:135], v[172:175], v[40:43]
	v_mfma_f32_16x16x32_bf16 v[28:31], v[124:127], v[180:183], v[28:31]
	v_mfma_f32_16x16x32_bf16 v[24:27], v[132:135], v[180:183], v[24:27]
	v_mfma_f32_16x16x32_bf16 v[12:15], v[124:127], v[188:191], v[12:15]
	v_mfma_f32_16x16x32_bf16 v[8:11], v[132:135], v[188:191], v[8:11]
	s_setprio 0
	s_setprio 1
	v_mfma_f32_16x16x32_bf16 v[52:55], v[140:143], v[160:163], v[52:55]
	v_mfma_f32_16x16x32_bf16 v[48:51], v[152:155], v[160:163], v[48:51]
	v_mfma_f32_16x16x32_bf16 v[36:39], v[140:143], v[168:171], v[36:39]
	v_mfma_f32_16x16x32_bf16 v[32:35], v[152:155], v[168:171], v[32:35]
	v_mfma_f32_16x16x32_bf16 v[20:23], v[140:143], v[176:179], v[20:23]
	v_mfma_f32_16x16x32_bf16 v[16:19], v[152:155], v[176:179], v[16:19]
	v_mfma_f32_16x16x32_bf16 v[4:7], v[140:143], v[184:187], v[4:7]
	v_mfma_f32_16x16x32_bf16 v[0:3], v[152:155], v[184:187], v[0:3]
	v_mfma_f32_16x16x32_bf16 v[52:55], v[148:151], v[164:167], v[52:55]
	v_mfma_f32_16x16x32_bf16 v[48:51], v[156:159], v[164:167], v[48:51]
	v_mfma_f32_16x16x32_bf16 v[36:39], v[148:151], v[172:175], v[36:39]
	v_mfma_f32_16x16x32_bf16 v[32:35], v[156:159], v[172:175], v[32:35]
	v_mfma_f32_16x16x32_bf16 v[20:23], v[148:151], v[180:183], v[20:23]
	v_mfma_f32_16x16x32_bf16 v[16:19], v[156:159], v[180:183], v[16:19]
	v_mfma_f32_16x16x32_bf16 v[4:7], v[148:151], v[188:191], v[4:7]
	v_mfma_f32_16x16x32_bf16 v[0:3], v[156:159], v[188:191], v[0:3]
	s_setprio 0
	s_barrier
	s_add_i32 s65, 0, 0x18000
	s_add_i32 s66, 0, 0x1c000
	s_add_u32 s34, s34, 0x40000
	s_addc_u32 s35, s35, 0
	s_mov_b32 m0, s39
	v_lshl_add_u64 v[214:215], s[34:35], 0, v[192:193]
	global_load_lds_dwordx4 v[214:215], off
	v_lshl_add_u64 v[214:215], s[34:35], 0, v[196:197]
	s_mov_b32 m0, s40
	s_nop 0
	global_load_lds_dwordx4 v[214:215], off
	v_add_u32_e32 v132, s65, v245
	v_add_u32_e32 v156, s66, v245
	ds_read_b128 v[120:123], v132
	ds_read_b128 v[124:127], v132 offset:1024
	ds_read_b128 v[128:131], v132 offset:2048
	ds_read_b128 v[132:135], v132 offset:3072
	ds_read_b128 v[140:143], v156
	ds_read_b128 v[148:151], v156 offset:1024
	ds_read_b128 v[152:155], v156 offset:2048
	ds_read_b128 v[156:159], v156 offset:3072
	ds_read_b128 v[160:163], v248 offset:32768
	ds_read_b128 v[164:167], v248 offset:33792
	ds_read_b128 v[168:171], v248 offset:34816
	ds_read_b128 v[172:175], v248 offset:35840
	ds_read_b128 v[176:179], v248 offset:36864
	ds_read_b128 v[180:183], v248 offset:37888
	ds_read_b128 v[184:187], v248 offset:38912
	ds_read_b128 v[188:191], v248 offset:39936
	s_waitcnt vmcnt(8)
	s_waitcnt lgkmcnt(0)
	s_barrier
	s_setprio 1
	s_waitcnt lgkmcnt(0)
	v_mfma_f32_16x16x32_bf16 v[144:147], v[120:123], v[160:163], v[144:147]
	v_mfma_f32_16x16x32_bf16 v[136:139], v[128:131], v[160:163], v[136:139]
	v_mfma_f32_16x16x32_bf16 v[108:111], v[120:123], v[168:171], v[108:111]
	v_mfma_f32_16x16x32_bf16 v[104:107], v[128:131], v[168:171], v[104:107]
	v_mfma_f32_16x16x32_bf16 v[92:95], v[120:123], v[176:179], v[92:95]
	v_mfma_f32_16x16x32_bf16 v[88:91], v[128:131], v[176:179], v[88:91]
	v_mfma_f32_16x16x32_bf16 v[76:79], v[120:123], v[184:187], v[76:79]
	v_mfma_f32_16x16x32_bf16 v[72:75], v[128:131], v[184:187], v[72:75]
	v_mfma_f32_16x16x32_bf16 v[144:147], v[124:127], v[164:167], v[144:147]
	v_mfma_f32_16x16x32_bf16 v[136:139], v[132:135], v[164:167], v[136:139]
	v_mfma_f32_16x16x32_bf16 v[108:111], v[124:127], v[172:175], v[108:111]
	v_mfma_f32_16x16x32_bf16 v[104:107], v[132:135], v[172:175], v[104:107]
	v_mfma_f32_16x16x32_bf16 v[92:95], v[124:127], v[180:183], v[92:95]
	v_mfma_f32_16x16x32_bf16 v[88:91], v[132:135], v[180:183], v[88:91]
	v_mfma_f32_16x16x32_bf16 v[76:79], v[124:127], v[188:191], v[76:79]
	v_mfma_f32_16x16x32_bf16 v[72:75], v[132:135], v[188:191], v[72:75]
	s_setprio 0
	s_setprio 1
	v_mfma_f32_16x16x32_bf16 v[116:119], v[140:143], v[160:163], v[116:119]
	v_mfma_f32_16x16x32_bf16 v[112:115], v[152:155], v[160:163], v[112:115]
	v_mfma_f32_16x16x32_bf16 v[100:103], v[140:143], v[168:171], v[100:103]
	v_mfma_f32_16x16x32_bf16 v[96:99], v[152:155], v[168:171], v[96:99]
	v_mfma_f32_16x16x32_bf16 v[84:87], v[140:143], v[176:179], v[84:87]
	v_mfma_f32_16x16x32_bf16 v[80:83], v[152:155], v[176:179], v[80:83]
	v_mfma_f32_16x16x32_bf16 v[68:71], v[140:143], v[184:187], v[68:71]
	v_mfma_f32_16x16x32_bf16 v[64:67], v[152:155], v[184:187], v[64:67]
	v_mfma_f32_16x16x32_bf16 v[116:119], v[148:151], v[164:167], v[116:119]
	v_mfma_f32_16x16x32_bf16 v[112:115], v[156:159], v[164:167], v[112:115]
	v_mfma_f32_16x16x32_bf16 v[100:103], v[148:151], v[172:175], v[100:103]
	v_mfma_f32_16x16x32_bf16 v[96:99], v[156:159], v[172:175], v[96:99]
	v_mfma_f32_16x16x32_bf16 v[84:87], v[148:151], v[180:183], v[84:87]
	v_mfma_f32_16x16x32_bf16 v[80:83], v[156:159], v[180:183], v[80:83]
	v_mfma_f32_16x16x32_bf16 v[68:71], v[148:151], v[188:191], v[68:71]
	v_mfma_f32_16x16x32_bf16 v[64:67], v[156:159], v[188:191], v[64:67]
	s_setprio 0
	s_barrier
	s_add_i32 s34, s65, s37
	v_lshl_add_u64 v[206:207], v[206:207], 0, s[12:13]
	s_mov_b32 m0, s34
	s_nop 0
	global_load_lds_dwordx4 v[206:207], off
	s_add_i32 m0, s34, 0x2000
	s_add_u32 s30, s30, 0x40080
	v_lshl_add_u64 v[206:207], v[208:209], 0, s[12:13]
	s_addc_u32 s31, s31, 0
	s_add_i32 s34, s66, s37
	global_load_lds_dwordx4 v[206:207], off
	v_lshl_add_u64 v[206:207], s[30:31], 0, v[194:195]
	s_mov_b32 m0, s34
	s_nop 0
	global_load_lds_dwordx4 v[206:207], off
	v_lshl_add_u64 v[206:207], s[30:31], 0, v[198:199]
	s_add_i32 m0, s34, 0x2000
	s_nop 0
	global_load_lds_dwordx4 v[206:207], off
	v_lshl_add_u64 v[206:207], v[210:211], 0, s[12:13]
	s_mov_b32 m0, s46
	s_nop 0
	global_load_lds_dwordx4 v[206:207], off
	v_lshl_add_u64 v[206:207], v[212:213], 0, s[12:13]
	s_mov_b32 m0, s47
	s_nop 0
	global_load_lds_dwordx4 v[206:207], off
	ds_read_b128 v[160:163], v248 offset:49152
	ds_read_b128 v[164:167], v248 offset:50176
	ds_read_b128 v[168:171], v248 offset:51200
	ds_read_b128 v[172:175], v248 offset:52224
	ds_read_b128 v[176:179], v248 offset:53248
	ds_read_b128 v[180:183], v248 offset:54272
	ds_read_b128 v[184:187], v248 offset:55296
	ds_read_b128 v[188:191], v248 offset:56320
	s_waitcnt vmcnt(8)
	s_waitcnt lgkmcnt(0)
	s_barrier
	s_setprio 1
	s_waitcnt lgkmcnt(0)
	v_mfma_f32_16x16x32_bf16 v[60:63], v[120:123], v[160:163], v[60:63]
	v_mfma_f32_16x16x32_bf16 v[56:59], v[128:131], v[160:163], v[56:59]
	v_mfma_f32_16x16x32_bf16 v[44:47], v[120:123], v[168:171], v[44:47]
	v_mfma_f32_16x16x32_bf16 v[40:43], v[128:131], v[168:171], v[40:43]
	v_mfma_f32_16x16x32_bf16 v[28:31], v[120:123], v[176:179], v[28:31]
	v_mfma_f32_16x16x32_bf16 v[24:27], v[128:131], v[176:179], v[24:27]
	v_mfma_f32_16x16x32_bf16 v[12:15], v[120:123], v[184:187], v[12:15]
	v_mfma_f32_16x16x32_bf16 v[8:11], v[128:131], v[184:187], v[8:11]
	v_mfma_f32_16x16x32_bf16 v[60:63], v[124:127], v[164:167], v[60:63]
	v_mfma_f32_16x16x32_bf16 v[56:59], v[132:135], v[164:167], v[56:59]
	v_mfma_f32_16x16x32_bf16 v[44:47], v[124:127], v[172:175], v[44:47]
	v_mfma_f32_16x16x32_bf16 v[40:43], v[132:135], v[172:175], v[40:43]
	v_mfma_f32_16x16x32_bf16 v[28:31], v[124:127], v[180:183], v[28:31]
	v_mfma_f32_16x16x32_bf16 v[24:27], v[132:135], v[180:183], v[24:27]
	v_mfma_f32_16x16x32_bf16 v[12:15], v[124:127], v[188:191], v[12:15]
	v_mfma_f32_16x16x32_bf16 v[8:11], v[132:135], v[188:191], v[8:11]
	s_setprio 0
	s_setprio 1
	v_mfma_f32_16x16x32_bf16 v[52:55], v[140:143], v[160:163], v[52:55]
	v_mfma_f32_16x16x32_bf16 v[48:51], v[152:155], v[160:163], v[48:51]
	v_mfma_f32_16x16x32_bf16 v[36:39], v[140:143], v[168:171], v[36:39]
	v_mfma_f32_16x16x32_bf16 v[32:35], v[152:155], v[168:171], v[32:35]
	v_mfma_f32_16x16x32_bf16 v[20:23], v[140:143], v[176:179], v[20:23]
	v_mfma_f32_16x16x32_bf16 v[16:19], v[152:155], v[176:179], v[16:19]
	v_mfma_f32_16x16x32_bf16 v[4:7], v[140:143], v[184:187], v[4:7]
	v_mfma_f32_16x16x32_bf16 v[0:3], v[152:155], v[184:187], v[0:3]
	v_mfma_f32_16x16x32_bf16 v[52:55], v[148:151], v[164:167], v[52:55]
	v_mfma_f32_16x16x32_bf16 v[48:51], v[156:159], v[164:167], v[48:51]
	v_mfma_f32_16x16x32_bf16 v[36:39], v[148:151], v[172:175], v[36:39]
	v_mfma_f32_16x16x32_bf16 v[32:35], v[156:159], v[172:175], v[32:35]
	v_mfma_f32_16x16x32_bf16 v[20:23], v[148:151], v[180:183], v[20:23]
	v_mfma_f32_16x16x32_bf16 v[16:19], v[156:159], v[180:183], v[16:19]
	v_mfma_f32_16x16x32_bf16 v[4:7], v[148:151], v[188:191], v[4:7]
	v_mfma_f32_16x16x32_bf16 v[0:3], v[156:159], v[188:191], v[0:3]
	s_setprio 0
	s_barrier
	s_add_i32 s64, s64, 2
	s_add_u32 s28, s28, 0x100
	s_addc_u32 s29, s29, 0
	s_add_u32 s62, s62, 0x100
	s_addc_u32 s63, s63, 0
	s_cmp_gt_u32 s64, 13
	s_cbranch_scc0 .LBB0_1109
	s_and_b64 vcc, exec, s[14:15]
	s_cbranch_vccz .LBB0_1112
	s_barrier

.LBB0_1193:
	s_add_u32 s30, s28, 0xfffc0080
	s_addc_u32 s31, s29, -1
	s_cmp_eq_u32 s62, 12
	s_cselect_b32 s35, s19, s31
	s_cselect_b32 s34, s50, s30
	s_cselect_b32 s31, s17, s61
	s_cselect_b32 s30, s51, s60
	v_lshl_add_u64 v[144:145], s[28:29], 0, v[136:137]
	s_add_i32 m0, s25, 0xc000
	s_nop 0
	global_load_lds_dwordx4 v[144:145], off
	v_lshl_add_u64 v[144:145], s[28:29], 0, v[138:139]
	s_add_i32 m0, s25, 0xe000
	s_nop 0
	global_load_lds_dwordx4 v[144:145], off
	ds_read_b128 v[154:157], v149
	ds_read_b128 v[158:161], v149 offset:1024
	ds_read_b128 v[162:165], v149 offset:2048
	ds_read_b128 v[166:169], v149 offset:3072
	ds_read_b128 v[170:173], v150
	ds_read_b128 v[174:177], v150 offset:1024
	ds_read_b128 v[178:181], v150 offset:2048
	ds_read_b128 v[182:185], v150 offset:3072
	ds_read_b128 v[186:189], v151
	ds_read_b128 v[190:193], v151 offset:1024
	ds_read_b128 v[194:197], v151 offset:2048
	ds_read_b128 v[198:201], v151 offset:3072
	ds_read_b128 v[202:205], v151 offset:4096
	ds_read_b128 v[206:209], v151 offset:5120
	ds_read_b128 v[210:213], v151 offset:6144
	ds_read_b128 v[214:217], v151 offset:7168
	s_waitcnt vmcnt(8)
	s_waitcnt lgkmcnt(0)
	s_barrier
	s_setprio 1
	s_waitcnt lgkmcnt(0)
	v_mfma_f32_16x16x32_bf16 v[116:119], v[154:157], v[186:189], v[116:119]
	v_mfma_f32_16x16x32_bf16 v[112:115], v[162:165], v[186:189], v[112:115]
	v_mfma_f32_16x16x32_bf16 v[108:111], v[154:157], v[194:197], v[108:111]
	v_mfma_f32_16x16x32_bf16 v[100:103], v[162:165], v[194:197], v[100:103]
	v_mfma_f32_16x16x32_bf16 v[92:95], v[154:157], v[202:205], v[92:95]
	v_mfma_f32_16x16x32_bf16 v[84:87], v[162:165], v[202:205], v[84:87]
	v_mfma_f32_16x16x32_bf16 v[76:79], v[154:157], v[210:213], v[76:79]
	v_mfma_f32_16x16x32_bf16 v[68:71], v[162:165], v[210:213], v[68:71]
	v_mfma_f32_16x16x32_bf16 v[116:119], v[158:161], v[190:193], v[116:119]
	v_mfma_f32_16x16x32_bf16 v[112:115], v[166:169], v[190:193], v[112:115]
	v_mfma_f32_16x16x32_bf16 v[108:111], v[158:161], v[198:201], v[108:111]
	v_mfma_f32_16x16x32_bf16 v[100:103], v[166:169], v[198:201], v[100:103]
	v_mfma_f32_16x16x32_bf16 v[92:95], v[158:161], v[206:209], v[92:95]
	v_mfma_f32_16x16x32_bf16 v[84:87], v[166:169], v[206:209], v[84:87]
	v_mfma_f32_16x16x32_bf16 v[76:79], v[158:161], v[214:217], v[76:79]
	v_mfma_f32_16x16x32_bf16 v[68:71], v[166:169], v[214:217], v[68:71]
	s_setprio 0
	s_setprio 1
	v_mfma_f32_16x16x32_bf16 v[124:127], v[170:173], v[186:189], v[124:127]
	v_mfma_f32_16x16x32_bf16 v[120:123], v[178:181], v[186:189], v[120:123]
	v_mfma_f32_16x16x32_bf16 v[104:107], v[170:173], v[194:197], v[104:107]
	v_mfma_f32_16x16x32_bf16 v[96:99], v[178:181], v[194:197], v[96:99]
	v_mfma_f32_16x16x32_bf16 v[88:91], v[170:173], v[202:205], v[88:91]
	v_mfma_f32_16x16x32_bf16 v[80:83], v[178:181], v[202:205], v[80:83]
	v_mfma_f32_16x16x32_bf16 v[72:75], v[170:173], v[210:213], v[72:75]
	v_mfma_f32_16x16x32_bf16 v[64:67], v[178:181], v[210:213], v[64:67]
	v_mfma_f32_16x16x32_bf16 v[124:127], v[174:177], v[190:193], v[124:127]
	v_mfma_f32_16x16x32_bf16 v[120:123], v[182:185], v[190:193], v[120:123]
	v_mfma_f32_16x16x32_bf16 v[104:107], v[174:177], v[198:201], v[104:107]
	v_mfma_f32_16x16x32_bf16 v[96:99], v[182:185], v[198:201], v[96:99]
	v_mfma_f32_16x16x32_bf16 v[88:91], v[174:177], v[206:209], v[88:91]
	v_mfma_f32_16x16x32_bf16 v[80:83], v[182:185], v[206:209], v[80:83]
	v_mfma_f32_16x16x32_bf16 v[72:75], v[174:177], v[214:217], v[72:75]
	v_mfma_f32_16x16x32_bf16 v[64:67], v[182:185], v[214:217], v[64:67]
	s_setprio 0
	s_barrier
	s_add_i32 s63, s47, s5
	v_lshl_add_u64 v[144:145], s[30:31], 0, v[132:133]
	s_mov_b32 m0, s63
	s_nop 0
	global_load_lds_dwordx4 v[144:145], off
	s_add_i32 m0, s63, 0x2000
	s_add_u32 s64, s30, 0x40000
	v_lshl_add_u64 v[218:219], s[30:31], 0, v[128:129]
	s_addc_u32 s65, s31, 0
	s_add_i32 s63, s48, s5
	global_load_lds_dwordx4 v[218:219], off
	v_lshl_add_u64 v[220:221], s[64:65], 0, v[132:133]
	s_mov_b32 m0, s63
	v_lshl_add_u64 v[222:223], s[34:35], 0, v[130:131]
	global_load_lds_dwordx4 v[220:221], off
	v_lshl_add_u64 v[220:221], s[64:65], 0, v[128:129]
	s_add_i32 m0, s63, 0x2000
	s_nop 0
	global_load_lds_dwordx4 v[220:221], off
	v_lshl_add_u64 v[220:221], s[34:35], 0, v[134:135]
	s_mov_b32 m0, s25
	s_nop 0
	global_load_lds_dwordx4 v[220:221], off
	s_mov_b32 m0, s27
	s_nop 0
	global_load_lds_dwordx4 v[222:223], off
	ds_read_b128 v[186:189], v151 offset:16384
	ds_read_b128 v[190:193], v151 offset:17408
	ds_read_b128 v[194:197], v151 offset:18432
	ds_read_b128 v[198:201], v151 offset:19456
	ds_read_b128 v[202:205], v151 offset:20480
	ds_read_b128 v[206:209], v151 offset:21504
	ds_read_b128 v[210:213], v151 offset:22528
	ds_read_b128 v[214:217], v151 offset:23552
	s_waitcnt vmcnt(8)
	s_waitcnt lgkmcnt(0)
	s_barrier
	s_setprio 1
	s_waitcnt lgkmcnt(0)
	v_mfma_f32_16x16x32_bf16 v[60:63], v[154:157], v[186:189], v[60:63]
	v_mfma_f32_16x16x32_bf16 v[52:55], v[162:165], v[186:189], v[52:55]
	v_mfma_f32_16x16x32_bf16 v[44:47], v[154:157], v[194:197], v[44:47]
	v_mfma_f32_16x16x32_bf16 v[36:39], v[162:165], v[194:197], v[36:39]
	v_mfma_f32_16x16x32_bf16 v[28:31], v[154:157], v[202:205], v[28:31]
	v_mfma_f32_16x16x32_bf16 v[20:23], v[162:165], v[202:205], v[20:23]
	v_mfma_f32_16x16x32_bf16 v[12:15], v[154:157], v[210:213], v[12:15]
	v_mfma_f32_16x16x32_bf16 v[4:7], v[162:165], v[210:213], v[4:7]
	v_mfma_f32_16x16x32_bf16 v[60:63], v[158:161], v[190:193], v[60:63]
	v_mfma_f32_16x16x32_bf16 v[52:55], v[166:169], v[190:193], v[52:55]
	v_mfma_f32_16x16x32_bf16 v[44:47], v[158:161], v[198:201], v[44:47]
	v_mfma_f32_16x16x32_bf16 v[36:39], v[166:169], v[198:201], v[36:39]
	v_mfma_f32_16x16x32_bf16 v[28:31], v[158:161], v[206:209], v[28:31]
	v_mfma_f32_16x16x32_bf16 v[20:23], v[166:169], v[206:209], v[20:23]
	v_mfma_f32_16x16x32_bf16 v[12:15], v[158:161], v[214:217], v[12:15]
	v_mfma_f32_16x16x32_bf16 v[4:7], v[166:169], v[214:217], v[4:7]
	s_setprio 0
	s_setprio 1
	v_mfma_f32_16x16x32_bf16 v[56:59], v[170:173], v[186:189], v[56:59]
	v_mfma_f32_16x16x32_bf16 v[48:51], v[178:181], v[186:189], v[48:51]
	v_mfma_f32_16x16x32_bf16 v[40:43], v[170:173], v[194:197], v[40:43]
	v_mfma_f32_16x16x32_bf16 v[32:35], v[178:181], v[194:197], v[32:35]
	v_mfma_f32_16x16x32_bf16 v[24:27], v[170:173], v[202:205], v[24:27]
	v_mfma_f32_16x16x32_bf16 v[16:19], v[178:181], v[202:205], v[16:19]
	v_mfma_f32_16x16x32_bf16 v[8:11], v[170:173], v[210:213], v[8:11]
	v_mfma_f32_16x16x32_bf16 v[0:3], v[178:181], v[210:213], v[0:3]
	v_mfma_f32_16x16x32_bf16 v[56:59], v[174:177], v[190:193], v[56:59]
	v_mfma_f32_16x16x32_bf16 v[48:51], v[182:185], v[190:193], v[48:51]
	v_mfma_f32_16x16x32_bf16 v[40:43], v[174:177], v[198:201], v[40:43]
	v_mfma_f32_16x16x32_bf16 v[32:35], v[182:185], v[198:201], v[32:35]
	v_mfma_f32_16x16x32_bf16 v[24:27], v[174:177], v[206:209], v[24:27]
	v_mfma_f32_16x16x32_bf16 v[16:19], v[182:185], v[206:209], v[16:19]
	v_mfma_f32_16x16x32_bf16 v[8:11], v[174:177], v[214:217], v[8:11]
	v_mfma_f32_16x16x32_bf16 v[0:3], v[182:185], v[214:217], v[0:3]
	s_setprio 0
	s_barrier
	s_add_i32 s63, 0, 0x18000
	s_add_i32 s64, 0, 0x1c000
	s_add_u32 s34, s34, 0x40000
	s_addc_u32 s35, s35, 0
	s_mov_b32 m0, s38
	v_lshl_add_u64 v[224:225], s[34:35], 0, v[134:135]
	global_load_lds_dwordx4 v[224:225], off
	v_lshl_add_u64 v[224:225], s[34:35], 0, v[130:131]
	s_mov_b32 m0, s39
	s_nop 0
	global_load_lds_dwordx4 v[224:225], off
	v_add_u32_e32 v153, s63, v147
	ds_read_b128 v[154:157], v153
	ds_read_b128 v[158:161], v153 offset:1024
	ds_read_b128 v[162:165], v153 offset:2048
	ds_read_b128 v[166:169], v153 offset:3072
	v_add_u32_e32 v153, s64, v147
	ds_read_b128 v[170:173], v153
	ds_read_b128 v[174:177], v153 offset:1024
	ds_read_b128 v[178:181], v153 offset:2048
	ds_read_b128 v[182:185], v153 offset:3072
	ds_read_b128 v[186:189], v151 offset:32768
	ds_read_b128 v[190:193], v151 offset:33792
	ds_read_b128 v[194:197], v151 offset:34816
	ds_read_b128 v[198:201], v151 offset:35840
	ds_read_b128 v[202:205], v151 offset:36864
	ds_read_b128 v[206:209], v151 offset:37888
	ds_read_b128 v[210:213], v151 offset:38912
	ds_read_b128 v[214:217], v151 offset:39936
	s_waitcnt vmcnt(8)
	s_waitcnt lgkmcnt(0)
	s_barrier
	s_setprio 1
	s_waitcnt lgkmcnt(0)
	v_mfma_f32_16x16x32_bf16 v[116:119], v[154:157], v[186:189], v[116:119]
	v_mfma_f32_16x16x32_bf16 v[112:115], v[162:165], v[186:189], v[112:115]
	v_mfma_f32_16x16x32_bf16 v[108:111], v[154:157], v[194:197], v[108:111]
	v_mfma_f32_16x16x32_bf16 v[100:103], v[162:165], v[194:197], v[100:103]
	v_mfma_f32_16x16x32_bf16 v[92:95], v[154:157], v[202:205], v[92:95]
	v_mfma_f32_16x16x32_bf16 v[84:87], v[162:165], v[202:205], v[84:87]
	v_mfma_f32_16x16x32_bf16 v[76:79], v[154:157], v[210:213], v[76:79]
	v_mfma_f32_16x16x32_bf16 v[68:71], v[162:165], v[210:213], v[68:71]
	v_mfma_f32_16x16x32_bf16 v[116:119], v[158:161], v[190:193], v[116:119]
	v_mfma_f32_16x16x32_bf16 v[112:115], v[166:169], v[190:193], v[112:115]
	v_mfma_f32_16x16x32_bf16 v[108:111], v[158:161], v[198:201], v[108:111]
	v_mfma_f32_16x16x32_bf16 v[100:103], v[166:169], v[198:201], v[100:103]
	v_mfma_f32_16x16x32_bf16 v[92:95], v[158:161], v[206:209], v[92:95]
	v_mfma_f32_16x16x32_bf16 v[84:87], v[166:169], v[206:209], v[84:87]
	v_mfma_f32_16x16x32_bf16 v[76:79], v[158:161], v[214:217], v[76:79]
	v_mfma_f32_16x16x32_bf16 v[68:71], v[166:169], v[214:217], v[68:71]
	s_setprio 0
	s_setprio 1
	v_mfma_f32_16x16x32_bf16 v[124:127], v[170:173], v[186:189], v[124:127]
	v_mfma_f32_16x16x32_bf16 v[120:123], v[178:181], v[186:189], v[120:123]
	v_mfma_f32_16x16x32_bf16 v[104:107], v[170:173], v[194:197], v[104:107]
	v_mfma_f32_16x16x32_bf16 v[96:99], v[178:181], v[194:197], v[96:99]
	v_mfma_f32_16x16x32_bf16 v[88:91], v[170:173], v[202:205], v[88:91]
	v_mfma_f32_16x16x32_bf16 v[80:83], v[178:181], v[202:205], v[80:83]
	v_mfma_f32_16x16x32_bf16 v[72:75], v[170:173], v[210:213], v[72:75]
	v_mfma_f32_16x16x32_bf16 v[64:67], v[178:181], v[210:213], v[64:67]
	v_mfma_f32_16x16x32_bf16 v[124:127], v[174:177], v[190:193], v[124:127]
	v_mfma_f32_16x16x32_bf16 v[120:123], v[182:185], v[190:193], v[120:123]
	v_mfma_f32_16x16x32_bf16 v[104:107], v[174:177], v[198:201], v[104:107]
	v_mfma_f32_16x16x32_bf16 v[96:99], v[182:185], v[198:201], v[96:99]
	v_mfma_f32_16x16x32_bf16 v[88:91], v[174:177], v[206:209], v[88:91]
	v_mfma_f32_16x16x32_bf16 v[80:83], v[182:185], v[206:209], v[80:83]
	v_mfma_f32_16x16x32_bf16 v[72:75], v[174:177], v[214:217], v[72:75]
	v_mfma_f32_16x16x32_bf16 v[64:67], v[182:185], v[214:217], v[64:67]
	s_setprio 0
	s_barrier
	s_add_i32 s34, s63, s5
	v_lshl_add_u64 v[144:145], v[144:145], 0, s[12:13]
	s_mov_b32 m0, s34
	s_nop 0
	global_load_lds_dwordx4 v[144:145], off
	s_add_i32 m0, s34, 0x2000
	s_add_u32 s30, s30, 0x40080
	v_lshl_add_u64 v[144:145], v[218:219], 0, s[12:13]
	s_addc_u32 s31, s31, 0
	s_add_i32 s34, s64, s5
	global_load_lds_dwordx4 v[144:145], off
	v_lshl_add_u64 v[144:145], s[30:31], 0, v[132:133]
	s_mov_b32 m0, s34
	s_nop 0
	global_load_lds_dwordx4 v[144:145], off
	v_lshl_add_u64 v[144:145], s[30:31], 0, v[128:129]
	s_add_i32 m0, s34, 0x2000
	s_nop 0
	global_load_lds_dwordx4 v[144:145], off
	v_lshl_add_u64 v[144:145], v[220:221], 0, s[12:13]
	s_mov_b32 m0, s41
	s_nop 0
	global_load_lds_dwordx4 v[144:145], off
	v_lshl_add_u64 v[144:145], v[222:223], 0, s[12:13]
	s_mov_b32 m0, s42
	s_nop 0
	global_load_lds_dwordx4 v[144:145], off
	ds_read_b128 v[186:189], v151 offset:49152
	ds_read_b128 v[190:193], v151 offset:50176
	ds_read_b128 v[194:197], v151 offset:51200
	ds_read_b128 v[198:201], v151 offset:52224
	ds_read_b128 v[202:205], v151 offset:53248
	ds_read_b128 v[206:209], v151 offset:54272
	ds_read_b128 v[210:213], v151 offset:55296
	ds_read_b128 v[214:217], v151 offset:56320
	s_waitcnt vmcnt(8)
	s_waitcnt lgkmcnt(0)
	s_barrier
	s_setprio 1
	s_waitcnt lgkmcnt(0)
	v_mfma_f32_16x16x32_bf16 v[60:63], v[154:157], v[186:189], v[60:63]
	v_mfma_f32_16x16x32_bf16 v[52:55], v[162:165], v[186:189], v[52:55]
	v_mfma_f32_16x16x32_bf16 v[44:47], v[154:157], v[194:197], v[44:47]
	v_mfma_f32_16x16x32_bf16 v[36:39], v[162:165], v[194:197], v[36:39]
	v_mfma_f32_16x16x32_bf16 v[28:31], v[154:157], v[202:205], v[28:31]
	v_mfma_f32_16x16x32_bf16 v[20:23], v[162:165], v[202:205], v[20:23]
	v_mfma_f32_16x16x32_bf16 v[12:15], v[154:157], v[210:213], v[12:15]
	v_mfma_f32_16x16x32_bf16 v[4:7], v[162:165], v[210:213], v[4:7]
	v_mfma_f32_16x16x32_bf16 v[60:63], v[158:161], v[190:193], v[60:63]
	v_mfma_f32_16x16x32_bf16 v[52:55], v[166:169], v[190:193], v[52:55]
	v_mfma_f32_16x16x32_bf16 v[44:47], v[158:161], v[198:201], v[44:47]
	v_mfma_f32_16x16x32_bf16 v[36:39], v[166:169], v[198:201], v[36:39]
	v_mfma_f32_16x16x32_bf16 v[28:31], v[158:161], v[206:209], v[28:31]
	v_mfma_f32_16x16x32_bf16 v[20:23], v[166:169], v[206:209], v[20:23]
	v_mfma_f32_16x16x32_bf16 v[12:15], v[158:161], v[214:217], v[12:15]
	v_mfma_f32_16x16x32_bf16 v[4:7], v[166:169], v[214:217], v[4:7]
	s_setprio 0
	s_setprio 1
	v_mfma_f32_16x16x32_bf16 v[56:59], v[170:173], v[186:189], v[56:59]
	v_mfma_f32_16x16x32_bf16 v[48:51], v[178:181], v[186:189], v[48:51]
	v_mfma_f32_16x16x32_bf16 v[40:43], v[170:173], v[194:197], v[40:43]
	v_mfma_f32_16x16x32_bf16 v[32:35], v[178:181], v[194:197], v[32:35]
	v_mfma_f32_16x16x32_bf16 v[24:27], v[170:173], v[202:205], v[24:27]
	v_mfma_f32_16x16x32_bf16 v[16:19], v[178:181], v[202:205], v[16:19]
	v_mfma_f32_16x16x32_bf16 v[8:11], v[170:173], v[210:213], v[8:11]
	v_mfma_f32_16x16x32_bf16 v[0:3], v[178:181], v[210:213], v[0:3]
	v_mfma_f32_16x16x32_bf16 v[56:59], v[174:177], v[190:193], v[56:59]
	v_mfma_f32_16x16x32_bf16 v[48:51], v[182:185], v[190:193], v[48:51]
	v_mfma_f32_16x16x32_bf16 v[40:43], v[174:177], v[198:201], v[40:43]
	v_mfma_f32_16x16x32_bf16 v[32:35], v[182:185], v[198:201], v[32:35]
	v_mfma_f32_16x16x32_bf16 v[24:27], v[174:177], v[206:209], v[24:27]
	v_mfma_f32_16x16x32_bf16 v[16:19], v[182:185], v[206:209], v[16:19]
	v_mfma_f32_16x16x32_bf16 v[8:11], v[174:177], v[214:217], v[8:11]
	v_mfma_f32_16x16x32_bf16 v[0:3], v[182:185], v[214:217], v[0:3]
	s_setprio 0
	s_barrier
	s_add_i32 s62, s62, 2
	s_add_u32 s28, s28, 0x100
	s_addc_u32 s29, s29, 0
	s_add_u32 s60, s60, 0x100
	s_addc_u32 s61, s61, 0
	s_cmp_gt_u32 s62, 13
	s_cbranch_scc0 .LBB0_1193
	s_and_b64 vcc, exec, s[14:15]
	s_cbranch_vccz .LBB0_1196
	s_barrier

.LBB0_1273:
	s_add_u32 s18, s16, 0x100
	s_addc_u32 s19, s17, 0
	s_cmp_eq_u32 s46, 40
	s_cselect_b32 s23, s5, s19
	s_cselect_b32 s22, s4, s18
	s_cselect_b32 s21, s15, s45
	s_cselect_b32 s20, s14, s44
	v_lshl_add_u64 v[192:193], s[16:17], 0, v[172:173]
	s_add_i32 m0, s26, 0xc000
	s_nop 0
	global_load_lds_dwordx4 v[192:193], off
	v_lshl_add_u64 v[192:193], s[16:17], 0, v[174:175]
	s_add_i32 m0, s26, 0xe000
	s_nop 0
	global_load_lds_dwordx4 v[192:193], off
	ds_read_b128 v[128:131], v197
	ds_read_b128 v[132:135], v197 offset:1024
	ds_read_b128 v[136:139], v197 offset:2048
	ds_read_b128 v[140:143], v197 offset:3072
	ds_read_b128 v[144:147], v198
	ds_read_b128 v[148:151], v198 offset:1024
	ds_read_b128 v[152:155], v198 offset:2048
	ds_read_b128 v[156:159], v198 offset:3072
	ds_read_b128 v[160:163], v199
	ds_read_b128 v[180:183], v199 offset:1024
	ds_read_b128 v[184:187], v199 offset:2048
	ds_read_b128 v[188:191], v199 offset:3072
	ds_read_b128 v[200:203], v199 offset:4096
	ds_read_b128 v[204:207], v199 offset:5120
	ds_read_b128 v[208:211], v199 offset:6144
	ds_read_b128 v[212:215], v199 offset:7168
	s_waitcnt vmcnt(8)
	s_waitcnt lgkmcnt(0)
	s_barrier
	s_setprio 1
	s_waitcnt lgkmcnt(0)
	v_mfma_f32_16x16x32_bf16 v[124:127], v[128:131], v[160:163], v[124:127]
	v_mfma_f32_16x16x32_bf16 v[120:123], v[136:139], v[160:163], v[120:123]
	v_mfma_f32_16x16x32_bf16 v[112:115], v[128:131], v[184:187], v[112:115]
	v_mfma_f32_16x16x32_bf16 v[104:107], v[136:139], v[184:187], v[104:107]
	v_mfma_f32_16x16x32_bf16 v[96:99], v[128:131], v[200:203], v[96:99]
	v_mfma_f32_16x16x32_bf16 v[88:91], v[136:139], v[200:203], v[88:91]
	v_mfma_f32_16x16x32_bf16 v[80:83], v[128:131], v[208:211], v[80:83]
	v_mfma_f32_16x16x32_bf16 v[72:75], v[136:139], v[208:211], v[72:75]
	v_mfma_f32_16x16x32_bf16 v[124:127], v[132:135], v[180:183], v[124:127]
	v_mfma_f32_16x16x32_bf16 v[120:123], v[140:143], v[180:183], v[120:123]
	v_mfma_f32_16x16x32_bf16 v[112:115], v[132:135], v[188:191], v[112:115]
	v_mfma_f32_16x16x32_bf16 v[104:107], v[140:143], v[188:191], v[104:107]
	v_mfma_f32_16x16x32_bf16 v[96:99], v[132:135], v[204:207], v[96:99]
	v_mfma_f32_16x16x32_bf16 v[88:91], v[140:143], v[204:207], v[88:91]
	v_mfma_f32_16x16x32_bf16 v[80:83], v[132:135], v[212:215], v[80:83]
	v_mfma_f32_16x16x32_bf16 v[72:75], v[140:143], v[212:215], v[72:75]
	s_setprio 0
	s_setprio 1
	v_mfma_f32_16x16x32_bf16 v[116:119], v[144:147], v[160:163], v[116:119]
	v_mfma_f32_16x16x32_bf16 v[108:111], v[152:155], v[160:163], v[108:111]
	v_mfma_f32_16x16x32_bf16 v[100:103], v[144:147], v[184:187], v[100:103]
	v_mfma_f32_16x16x32_bf16 v[92:95], v[152:155], v[184:187], v[92:95]
	v_mfma_f32_16x16x32_bf16 v[84:87], v[144:147], v[200:203], v[84:87]
	v_mfma_f32_16x16x32_bf16 v[76:79], v[152:155], v[200:203], v[76:79]
	v_mfma_f32_16x16x32_bf16 v[68:71], v[144:147], v[208:211], v[68:71]
	v_mfma_f32_16x16x32_bf16 v[64:67], v[152:155], v[208:211], v[64:67]
	v_mfma_f32_16x16x32_bf16 v[116:119], v[148:151], v[180:183], v[116:119]
	v_mfma_f32_16x16x32_bf16 v[108:111], v[156:159], v[180:183], v[108:111]
	v_mfma_f32_16x16x32_bf16 v[100:103], v[148:151], v[188:191], v[100:103]
	v_mfma_f32_16x16x32_bf16 v[92:95], v[156:159], v[188:191], v[92:95]
	v_mfma_f32_16x16x32_bf16 v[84:87], v[148:151], v[204:207], v[84:87]
	v_mfma_f32_16x16x32_bf16 v[76:79], v[156:159], v[204:207], v[76:79]
	v_mfma_f32_16x16x32_bf16 v[68:71], v[148:151], v[212:215], v[68:71]
	v_mfma_f32_16x16x32_bf16 v[64:67], v[156:159], v[212:215], v[64:67]
	s_setprio 0
	s_barrier
	s_add_i32 s16, s38, s25
	v_lshl_add_u64 v[192:193], s[20:21], 0, v[166:167]
	s_mov_b32 m0, s16
	s_nop 0
	global_load_lds_dwordx4 v[192:193], off
	s_add_i32 m0, s16, 0x2000
	s_add_u32 s16, s20, 0xb0000
	v_lshl_add_u64 v[216:217], s[20:21], 0, v[170:171]
	s_addc_u32 s17, s21, 0
	s_add_i32 s47, s39, s25
	global_load_lds_dwordx4 v[216:217], off
	v_lshl_add_u64 v[218:219], s[16:17], 0, v[166:167]
	s_mov_b32 m0, s47
	v_lshl_add_u64 v[220:221], s[22:23], 0, v[168:169]
	global_load_lds_dwordx4 v[218:219], off
	v_lshl_add_u64 v[218:219], s[16:17], 0, v[170:171]
	s_add_i32 m0, s47, 0x2000
	s_nop 0
	global_load_lds_dwordx4 v[218:219], off
	v_lshl_add_u64 v[218:219], s[22:23], 0, v[164:165]
	s_mov_b32 m0, s26
	s_nop 0
	global_load_lds_dwordx4 v[218:219], off
	s_mov_b32 m0, s27
	s_nop 0
	global_load_lds_dwordx4 v[220:221], off
	ds_read_b128 v[160:163], v199 offset:16384
	ds_read_b128 v[180:183], v199 offset:17408
	ds_read_b128 v[184:187], v199 offset:18432
	ds_read_b128 v[188:191], v199 offset:19456
	ds_read_b128 v[200:203], v199 offset:20480
	ds_read_b128 v[204:207], v199 offset:21504
	ds_read_b128 v[208:211], v199 offset:22528
	ds_read_b128 v[212:215], v199 offset:23552
	s_waitcnt vmcnt(8)
	s_waitcnt lgkmcnt(0)
	s_barrier
	s_setprio 1
	s_waitcnt lgkmcnt(0)
	v_mfma_f32_16x16x32_bf16 v[60:63], v[128:131], v[160:163], v[60:63]
	v_mfma_f32_16x16x32_bf16 v[56:59], v[136:139], v[160:163], v[56:59]
	v_mfma_f32_16x16x32_bf16 v[48:51], v[128:131], v[184:187], v[48:51]
	v_mfma_f32_16x16x32_bf16 v[40:43], v[136:139], v[184:187], v[40:43]
	v_mfma_f32_16x16x32_bf16 v[32:35], v[128:131], v[200:203], v[32:35]
	v_mfma_f32_16x16x32_bf16 v[24:27], v[136:139], v[200:203], v[24:27]
	v_mfma_f32_16x16x32_bf16 v[16:19], v[128:131], v[208:211], v[16:19]
	v_mfma_f32_16x16x32_bf16 v[8:11], v[136:139], v[208:211], v[8:11]
	v_mfma_f32_16x16x32_bf16 v[60:63], v[132:135], v[180:183], v[60:63]
	v_mfma_f32_16x16x32_bf16 v[56:59], v[140:143], v[180:183], v[56:59]
	v_mfma_f32_16x16x32_bf16 v[48:51], v[132:135], v[188:191], v[48:51]
	v_mfma_f32_16x16x32_bf16 v[40:43], v[140:143], v[188:191], v[40:43]
	v_mfma_f32_16x16x32_bf16 v[32:35], v[132:135], v[204:207], v[32:35]
	v_mfma_f32_16x16x32_bf16 v[24:27], v[140:143], v[204:207], v[24:27]
	v_mfma_f32_16x16x32_bf16 v[16:19], v[132:135], v[212:215], v[16:19]
	v_mfma_f32_16x16x32_bf16 v[8:11], v[140:143], v[212:215], v[8:11]
	s_setprio 0
	s_setprio 1
	v_mfma_f32_16x16x32_bf16 v[52:55], v[144:147], v[160:163], v[52:55]
	v_mfma_f32_16x16x32_bf16 v[44:47], v[152:155], v[160:163], v[44:47]
	v_mfma_f32_16x16x32_bf16 v[36:39], v[144:147], v[184:187], v[36:39]
	v_mfma_f32_16x16x32_bf16 v[28:31], v[152:155], v[184:187], v[28:31]
	v_mfma_f32_16x16x32_bf16 v[20:23], v[144:147], v[200:203], v[20:23]
	v_mfma_f32_16x16x32_bf16 v[12:15], v[152:155], v[200:203], v[12:15]
	v_mfma_f32_16x16x32_bf16 v[4:7], v[144:147], v[208:211], v[4:7]
	v_mfma_f32_16x16x32_bf16 v[0:3], v[152:155], v[208:211], v[0:3]
	v_mfma_f32_16x16x32_bf16 v[52:55], v[148:151], v[180:183], v[52:55]
	v_mfma_f32_16x16x32_bf16 v[44:47], v[156:159], v[180:183], v[44:47]
	v_mfma_f32_16x16x32_bf16 v[36:39], v[148:151], v[188:191], v[36:39]
	v_mfma_f32_16x16x32_bf16 v[28:31], v[156:159], v[188:191], v[28:31]
	v_mfma_f32_16x16x32_bf16 v[20:23], v[148:151], v[204:207], v[20:23]
	v_mfma_f32_16x16x32_bf16 v[12:15], v[156:159], v[204:207], v[12:15]
	v_mfma_f32_16x16x32_bf16 v[4:7], v[148:151], v[212:215], v[4:7]
	v_mfma_f32_16x16x32_bf16 v[0:3], v[156:159], v[212:215], v[0:3]
	s_setprio 0
	s_barrier
	s_add_i32 s47, 0, 0x18000
	s_add_i32 s48, 0, 0x1c000
	s_add_u32 s16, s22, 0xb0000
	s_addc_u32 s17, s23, 0
	s_mov_b32 m0, s28
	v_lshl_add_u64 v[222:223], s[16:17], 0, v[164:165]
	global_load_lds_dwordx4 v[222:223], off
	v_lshl_add_u64 v[222:223], s[16:17], 0, v[168:169]
	s_mov_b32 m0, s29
	s_nop 0
	global_load_lds_dwordx4 v[222:223], off
	v_add_u32_e32 v140, s47, v196
	v_add_u32_e32 v156, s48, v196
	ds_read_b128 v[128:131], v140
	ds_read_b128 v[132:135], v140 offset:1024
	ds_read_b128 v[136:139], v140 offset:2048
	ds_read_b128 v[140:143], v140 offset:3072
	ds_read_b128 v[144:147], v156
	ds_read_b128 v[148:151], v156 offset:1024
	ds_read_b128 v[152:155], v156 offset:2048
	ds_read_b128 v[156:159], v156 offset:3072
	ds_read_b128 v[160:163], v199 offset:32768
	ds_read_b128 v[180:183], v199 offset:33792
	ds_read_b128 v[184:187], v199 offset:34816
	ds_read_b128 v[188:191], v199 offset:35840
	ds_read_b128 v[200:203], v199 offset:36864
	ds_read_b128 v[204:207], v199 offset:37888
	ds_read_b128 v[208:211], v199 offset:38912
	ds_read_b128 v[212:215], v199 offset:39936
	s_waitcnt vmcnt(8)
	s_waitcnt lgkmcnt(0)
	s_barrier
	s_setprio 1
	s_waitcnt lgkmcnt(0)
	v_mfma_f32_16x16x32_bf16 v[124:127], v[128:131], v[160:163], v[124:127]
	v_mfma_f32_16x16x32_bf16 v[120:123], v[136:139], v[160:163], v[120:123]
	v_mfma_f32_16x16x32_bf16 v[112:115], v[128:131], v[184:187], v[112:115]
	v_mfma_f32_16x16x32_bf16 v[104:107], v[136:139], v[184:187], v[104:107]
	v_mfma_f32_16x16x32_bf16 v[96:99], v[128:131], v[200:203], v[96:99]
	v_mfma_f32_16x16x32_bf16 v[88:91], v[136:139], v[200:203], v[88:91]
	v_mfma_f32_16x16x32_bf16 v[80:83], v[128:131], v[208:211], v[80:83]
	v_mfma_f32_16x16x32_bf16 v[72:75], v[136:139], v[208:211], v[72:75]
	v_mfma_f32_16x16x32_bf16 v[124:127], v[132:135], v[180:183], v[124:127]
	v_mfma_f32_16x16x32_bf16 v[120:123], v[140:143], v[180:183], v[120:123]
	v_mfma_f32_16x16x32_bf16 v[112:115], v[132:135], v[188:191], v[112:115]
	v_mfma_f32_16x16x32_bf16 v[104:107], v[140:143], v[188:191], v[104:107]
	v_mfma_f32_16x16x32_bf16 v[96:99], v[132:135], v[204:207], v[96:99]
	v_mfma_f32_16x16x32_bf16 v[88:91], v[140:143], v[204:207], v[88:91]
	v_mfma_f32_16x16x32_bf16 v[80:83], v[132:135], v[212:215], v[80:83]
	v_mfma_f32_16x16x32_bf16 v[72:75], v[140:143], v[212:215], v[72:75]
	s_setprio 0
	s_setprio 1
	v_mfma_f32_16x16x32_bf16 v[116:119], v[144:147], v[160:163], v[116:119]
	v_mfma_f32_16x16x32_bf16 v[108:111], v[152:155], v[160:163], v[108:111]
	v_mfma_f32_16x16x32_bf16 v[100:103], v[144:147], v[184:187], v[100:103]
	v_mfma_f32_16x16x32_bf16 v[92:95], v[152:155], v[184:187], v[92:95]
	v_mfma_f32_16x16x32_bf16 v[84:87], v[144:147], v[200:203], v[84:87]
	v_mfma_f32_16x16x32_bf16 v[76:79], v[152:155], v[200:203], v[76:79]
	v_mfma_f32_16x16x32_bf16 v[68:71], v[144:147], v[208:211], v[68:71]
	v_mfma_f32_16x16x32_bf16 v[64:67], v[152:155], v[208:211], v[64:67]
	v_mfma_f32_16x16x32_bf16 v[116:119], v[148:151], v[180:183], v[116:119]
	v_mfma_f32_16x16x32_bf16 v[108:111], v[156:159], v[180:183], v[108:111]
	v_mfma_f32_16x16x32_bf16 v[100:103], v[148:151], v[188:191], v[100:103]
	v_mfma_f32_16x16x32_bf16 v[92:95], v[156:159], v[188:191], v[92:95]
	v_mfma_f32_16x16x32_bf16 v[84:87], v[148:151], v[204:207], v[84:87]
	v_mfma_f32_16x16x32_bf16 v[76:79], v[156:159], v[204:207], v[76:79]
	v_mfma_f32_16x16x32_bf16 v[68:71], v[148:151], v[212:215], v[68:71]
	v_mfma_f32_16x16x32_bf16 v[64:67], v[156:159], v[212:215], v[64:67]
	s_setprio 0
	s_barrier
	s_add_i32 s16, s47, s25
	v_lshl_add_u64 v[192:193], v[192:193], 0, s[10:11]
	s_mov_b32 m0, s16
	s_nop 0
	global_load_lds_dwordx4 v[192:193], off
	s_add_i32 m0, s16, 0x2000
	s_add_u32 s16, s20, 0xb0080
	v_lshl_add_u64 v[192:193], v[216:217], 0, s[10:11]
	s_addc_u32 s17, s21, 0
	s_add_i32 s20, s48, s25
	global_load_lds_dwordx4 v[192:193], off
	v_lshl_add_u64 v[192:193], s[16:17], 0, v[166:167]
	s_mov_b32 m0, s20
	s_nop 0
	global_load_lds_dwordx4 v[192:193], off
	v_lshl_add_u64 v[192:193], s[16:17], 0, v[170:171]
	s_add_i32 m0, s20, 0x2000
	s_nop 0
	global_load_lds_dwordx4 v[192:193], off
	v_lshl_add_u64 v[192:193], v[218:219], 0, s[10:11]
	s_mov_b32 m0, s35
	s_nop 0
	global_load_lds_dwordx4 v[192:193], off
	v_lshl_add_u64 v[192:193], v[220:221], 0, s[10:11]
	s_mov_b32 m0, s36
	s_nop 0
	global_load_lds_dwordx4 v[192:193], off
	ds_read_b128 v[160:163], v199 offset:49152
	ds_read_b128 v[180:183], v199 offset:50176
	ds_read_b128 v[184:187], v199 offset:51200
	ds_read_b128 v[188:191], v199 offset:52224
	ds_read_b128 v[200:203], v199 offset:53248
	ds_read_b128 v[204:207], v199 offset:54272
	ds_read_b128 v[208:211], v199 offset:55296
	ds_read_b128 v[212:215], v199 offset:56320
	s_waitcnt vmcnt(8)
	s_waitcnt lgkmcnt(0)
	s_barrier
	s_setprio 1
	s_waitcnt lgkmcnt(0)
	v_mfma_f32_16x16x32_bf16 v[60:63], v[128:131], v[160:163], v[60:63]
	v_mfma_f32_16x16x32_bf16 v[56:59], v[136:139], v[160:163], v[56:59]
	v_mfma_f32_16x16x32_bf16 v[48:51], v[128:131], v[184:187], v[48:51]
	v_mfma_f32_16x16x32_bf16 v[40:43], v[136:139], v[184:187], v[40:43]
	v_mfma_f32_16x16x32_bf16 v[32:35], v[128:131], v[200:203], v[32:35]
	v_mfma_f32_16x16x32_bf16 v[24:27], v[136:139], v[200:203], v[24:27]
	v_mfma_f32_16x16x32_bf16 v[16:19], v[128:131], v[208:211], v[16:19]
	v_mfma_f32_16x16x32_bf16 v[8:11], v[136:139], v[208:211], v[8:11]
	v_mfma_f32_16x16x32_bf16 v[60:63], v[132:135], v[180:183], v[60:63]
	v_mfma_f32_16x16x32_bf16 v[56:59], v[140:143], v[180:183], v[56:59]
	v_mfma_f32_16x16x32_bf16 v[48:51], v[132:135], v[188:191], v[48:51]
	v_mfma_f32_16x16x32_bf16 v[40:43], v[140:143], v[188:191], v[40:43]
	v_mfma_f32_16x16x32_bf16 v[32:35], v[132:135], v[204:207], v[32:35]
	v_mfma_f32_16x16x32_bf16 v[24:27], v[140:143], v[204:207], v[24:27]
	v_mfma_f32_16x16x32_bf16 v[16:19], v[132:135], v[212:215], v[16:19]
	v_mfma_f32_16x16x32_bf16 v[8:11], v[140:143], v[212:215], v[8:11]
	s_setprio 0
	s_setprio 1
	v_mfma_f32_16x16x32_bf16 v[52:55], v[144:147], v[160:163], v[52:55]
	v_mfma_f32_16x16x32_bf16 v[44:47], v[152:155], v[160:163], v[44:47]
	v_mfma_f32_16x16x32_bf16 v[36:39], v[144:147], v[184:187], v[36:39]
	v_mfma_f32_16x16x32_bf16 v[28:31], v[152:155], v[184:187], v[28:31]
	v_mfma_f32_16x16x32_bf16 v[20:23], v[144:147], v[200:203], v[20:23]
	v_mfma_f32_16x16x32_bf16 v[12:15], v[152:155], v[200:203], v[12:15]
	v_mfma_f32_16x16x32_bf16 v[4:7], v[144:147], v[208:211], v[4:7]
	v_mfma_f32_16x16x32_bf16 v[0:3], v[152:155], v[208:211], v[0:3]
	v_mfma_f32_16x16x32_bf16 v[52:55], v[148:151], v[180:183], v[52:55]
	v_mfma_f32_16x16x32_bf16 v[44:47], v[156:159], v[180:183], v[44:47]
	v_mfma_f32_16x16x32_bf16 v[36:39], v[148:151], v[188:191], v[36:39]
	v_mfma_f32_16x16x32_bf16 v[28:31], v[156:159], v[188:191], v[28:31]
	v_mfma_f32_16x16x32_bf16 v[20:23], v[148:151], v[204:207], v[20:23]
	v_mfma_f32_16x16x32_bf16 v[12:15], v[156:159], v[204:207], v[12:15]
	v_mfma_f32_16x16x32_bf16 v[4:7], v[148:151], v[212:215], v[4:7]
	v_mfma_f32_16x16x32_bf16 v[0:3], v[156:159], v[212:215], v[0:3]
	s_setprio 0
	s_barrier
	s_add_i32 s46, s46, 2
	s_add_u32 s44, s44, 0x100
	s_addc_u32 s45, s45, 0
	s_cmp_gt_u32 s46, 41
	s_mov_b64 s[16:17], s[18:19]
	s_cbranch_scc0 .LBB0_1273
	s_and_b64 vcc, exec, s[12:13]
	s_cbranch_vccz .LBB0_1276
	s_barrier
